# P9 expert gate/up K-loop: same 2-set ping-pong / rotated-barrier structure; next-tile prefetch issued after the last MFMA group
# speedup vs baseline: 1.0332x; 1.0149x over previous
; DI void wait_vm0() { asm volatile("s_waitcnt vmcnt(0)" ::: "memory"); }
; template <int TM, int TN, int WM, int WN, bool SUMSQ, int NST, class AF, class BF, class AFN, class BFN>
; DI void gemm8x(f32x16 (&acc)[TM][TN], AF arow, BF brow, int K, char* smem, float& sumsq, bool pre, bool hasNext, AFN arowN, BFN browN) {
;     ...
;   const int t = tid_(), lane = t & 63, w = t >> 6, r = lane & 31, hh = lane >> 5;
;   const int wm = w % WM, wn = w / WM;
;   const int row0 = t >> 3;
;   const int c = (t & 7) ^ ((row0 >> 1) & 7);
;   const bool a0v = row0 < RA, a1v = row0 + 64 < RA, a2v = row0 + 128 < RA, a3v = row0 + 192 < RA;
;   const bool b0v = row0 < RB, b1v = row0 + 64 < RB, b2v = row0 + 128 < RB, b3v = row0 + 192 < RB;
;   const bf16_t* pa0 = arow(a0v ? row0 : 0) + c * 8;
;   const bf16_t* pa1 = arow(a1v ? row0 + 64 : 0) + c * 8;
;   const bf16_t* pa2 = arow(a2v ? row0 + 128 : 0) + c * 8;
;   const bf16_t* pa3 = arow(a3v ? row0 + 192 : 0) + c * 8;
;   const bf16_t* pb0 = brow(b0v ? row0 : 0) + c * 8;
;   const bf16_t* pb1 = brow(b1v ? row0 + 64 : 0) + c * 8;
;   const bf16_t* pb2 = brow(b2v ? row0 + 128 : 0) + c * 8;
;   const bf16_t* pb3 = brow(b3v ? row0 + 192 : 0) + c * 8;
;   if (!pre) {
;     char* l_ = smem + t * 16; char* m_ = l_ + RA * LDR;
;     if (a0v) GLDS(pa0, l_); if (a1v) GLDS(pa1, l_ + 8192); if (a2v) GLDS(pa2, l_ + 16384); if (a3v) GLDS(pa3, l_ + 24576);
;     if (b0v) GLDS(pb0, m_); if (b1v) GLDS(pb1, m_ + 8192); if (b2v) GLDS(pb2, m_ + 16384); if (b3v) GLDS(pb3, m_ + 24576);
;   }
;   if (NST == 3) {
;     char* l_ = smem + STAGE + t * 16; char* m_ = l_ + RA * LDR;
;     GLDS(pa0 + 64, l_); GLDS(pa1 + 64, l_ + 8192); GLDS(pa2 + 64, l_ + 16384); GLDS(pa3 + 64, l_ + 24576);
;     GLDS(pb0 + 64, m_); GLDS(pb1 + 64, m_ + 8192);
;     asm volatile("s_waitcnt vmcnt(6)" ::: "memory");
;   } else wait_vm0();
;   bar_();
;   const int nk = K >> 6;
;   const int sw = (r >> 1) & 7;
;   const int aoff = (wm * TM * 32 + r) * LDR, boff = RA * LDR + (wn * TN * 32 + r) * LDR;
; DI void phase9_10(const Params& p, char* smem) {
;     ...
;       f32x16 acc[4][2];
; #pragma unroll
;       for (int a = 0; a < 4; ++a)
; #pragma unroll
;         for (int c = 0; c < 2; ++c) acc[a][c] = zero16();
;       float dummy = 0.f;
;       gemm8x<4, 2, 2, 4, false, 2>(acc, [&](int row) { return Ab + (size_t)row * DM; }, [&](int row) { return hb + (size_t)ib[row] * DM; }, DM, smem, dummy,
.LBB0_1201:
	v_ashrrev_i32_e32 v10, 6, v8
	v_lshrrev_b32_e32 v12, 31, v8
	v_add_u32_e32 v12, v10, v12
	v_and_b32_e32 v13, 0x3fffe, v12
	v_bfe_u32 v11, v8, 5, 1
	v_sub_u32_e32 v10, v10, v13
	v_lshrrev_b32_e32 v13, 1, v8
	v_bfe_u32 v14, v8, 1, 3
	v_lshlrev_b32_e32 v8, 7, v8
	v_and_b32_e32 v229, 0xf80, v8
	v_lshlrev_b32_e32 v8, 12, v12
	v_and_b32_e32 v230, 0xffffe000, v8
	v_bitop3_b32 v8, v13, v11, 7 bitop3:0x6c
	v_lshlrev_b32_e32 v227, 4, v8
	v_bitop3_b32 v8, v11, v14, 2 bitop3:0x36
	v_lshlrev_b32_e32 v226, 4, v8
	v_bitop3_b32 v8, v11, v14, 4 bitop3:0x36
	v_lshlrev_b32_e32 v225, 4, v8
	v_bitop3_b32 v8, v11, v14, 6 bitop3:0x36
	v_lshlrev_b32_e32 v224, 4, v8
	v_and_b32_e32 v8, 7, v9
	v_lshlrev_b32_e32 v8, 4, v8
	v_mov_b32_e32 v9, v185
	v_lshl_add_u64 v[0:1], v[0:1], 0, v[8:9]
	v_lshl_or_b32 v228, v10, 14, v229
	v_lshl_add_u64 v[10:11], v[196:197], 0, v[8:9]
	v_lshl_add_u64 v[212:213], s[50:51], 0, v[0:1]
	v_lshl_add_u64 v[0:1], v[6:7], 0, v[8:9]
	v_lshl_add_u64 v[204:205], s[44:45], 0, v[10:11]
	v_lshl_add_u64 v[10:11], v[198:199], 0, v[8:9]
	v_lshl_add_u64 v[214:215], s[50:51], 0, v[0:1]
	v_lshl_add_u64 v[0:1], v[4:5], 0, v[8:9]
	s_waitcnt vmcnt(0)
	v_lshl_add_u64 v[206:207], s[44:45], 0, v[10:11]
	v_lshl_add_u64 v[10:11], v[200:201], 0, v[8:9]
	v_lshl_add_u64 v[216:217], s[50:51], 0, v[0:1]
	v_lshl_add_u64 v[0:1], v[2:3], 0, v[8:9]
	v_lshl_add_u64 v[208:209], s[44:45], 0, v[10:11]
	v_lshl_add_u64 v[10:11], v[202:203], 0, v[8:9]
	v_lshl_add_u64 v[218:219], s[50:51], 0, v[0:1]
	v_mov_b32_e32 v0, 0
	v_or_b32_e32 v231, v229, v230
	v_lshl_add_u64 v[210:211], s[44:45], 0, v[10:11]
	s_mov_b32 s80, 0
	s_mov_b64 s[52:53], 0
	v_mov_b32_e32 v1, v0
	v_mov_b32_e32 v2, v0
	v_mov_b32_e32 v3, v0
	v_mov_b32_e32 v4, v0
	v_mov_b32_e32 v5, v0
	v_mov_b32_e32 v6, v0
	v_mov_b32_e32 v7, v0
	v_mov_b32_e32 v8, v0
	v_mov_b32_e32 v9, v0
	v_mov_b32_e32 v10, v0
	v_mov_b32_e32 v11, v0
	v_mov_b32_e32 v12, v0
	v_mov_b32_e32 v13, v0
	v_mov_b32_e32 v14, v0
	v_mov_b32_e32 v15, v0
	v_mov_b32_e32 v64, v0
	v_mov_b32_e32 v65, v0
	v_mov_b32_e32 v66, v0
	v_mov_b32_e32 v67, v0
	v_mov_b32_e32 v68, v0
	v_mov_b32_e32 v69, v0
	v_mov_b32_e32 v70, v0
	v_mov_b32_e32 v71, v0
	v_mov_b32_e32 v72, v0
	v_mov_b32_e32 v73, v0
	v_mov_b32_e32 v74, v0
	v_mov_b32_e32 v75, v0
	v_mov_b32_e32 v76, v0
	v_mov_b32_e32 v77, v0
	v_mov_b32_e32 v78, v0
	v_mov_b32_e32 v79, v0
	v_mov_b32_e32 v16, v0
	v_mov_b32_e32 v17, v0
	v_mov_b32_e32 v18, v0
	v_mov_b32_e32 v19, v0
	v_mov_b32_e32 v20, v0
	v_mov_b32_e32 v21, v0
	v_mov_b32_e32 v22, v0
	v_mov_b32_e32 v23, v0
	v_mov_b32_e32 v24, v0
	v_mov_b32_e32 v25, v0
	v_mov_b32_e32 v26, v0
	v_mov_b32_e32 v27, v0
	v_mov_b32_e32 v28, v0
	v_mov_b32_e32 v29, v0
	v_mov_b32_e32 v30, v0
	v_mov_b32_e32 v31, v0
	v_mov_b32_e32 v80, v0
	v_mov_b32_e32 v81, v0
	v_mov_b32_e32 v82, v0
	v_mov_b32_e32 v83, v0
	v_mov_b32_e32 v84, v0
	v_mov_b32_e32 v85, v0
	v_mov_b32_e32 v86, v0
	v_mov_b32_e32 v87, v0
	v_mov_b32_e32 v88, v0
	v_mov_b32_e32 v89, v0
	v_mov_b32_e32 v90, v0
	v_mov_b32_e32 v91, v0
	v_mov_b32_e32 v92, v0
	v_mov_b32_e32 v93, v0
	v_mov_b32_e32 v94, v0
	v_mov_b32_e32 v95, v0
	v_mov_b32_e32 v32, v0
	v_mov_b32_e32 v33, v0
	v_mov_b32_e32 v34, v0
	v_mov_b32_e32 v35, v0
	v_mov_b32_e32 v36, v0
	v_mov_b32_e32 v37, v0
	v_mov_b32_e32 v38, v0
	v_mov_b32_e32 v39, v0
	v_mov_b32_e32 v40, v0
	v_mov_b32_e32 v41, v0
	v_mov_b32_e32 v42, v0
	v_mov_b32_e32 v43, v0
	v_mov_b32_e32 v44, v0
	v_mov_b32_e32 v45, v0
	v_mov_b32_e32 v46, v0
	v_mov_b32_e32 v47, v0
	v_mov_b32_e32 v96, v0
	v_mov_b32_e32 v97, v0
	v_mov_b32_e32 v98, v0
	v_mov_b32_e32 v99, v0
	v_mov_b32_e32 v100, v0
	v_mov_b32_e32 v101, v0
	v_mov_b32_e32 v102, v0
	v_mov_b32_e32 v103, v0
	v_mov_b32_e32 v104, v0
	v_mov_b32_e32 v105, v0
	v_mov_b32_e32 v106, v0
	v_mov_b32_e32 v107, v0
	v_mov_b32_e32 v108, v0
	v_mov_b32_e32 v109, v0
	v_mov_b32_e32 v110, v0
	v_mov_b32_e32 v111, v0
	v_mov_b32_e32 v48, v0
	v_mov_b32_e32 v49, v0
	v_mov_b32_e32 v50, v0
	v_mov_b32_e32 v51, v0
	v_mov_b32_e32 v52, v0
	v_mov_b32_e32 v53, v0
	v_mov_b32_e32 v54, v0
	v_mov_b32_e32 v55, v0
	v_mov_b32_e32 v56, v0
	v_mov_b32_e32 v57, v0
	v_mov_b32_e32 v58, v0
	v_mov_b32_e32 v59, v0
	v_mov_b32_e32 v60, v0
	v_mov_b32_e32 v61, v0
	v_mov_b32_e32 v62, v0
	v_mov_b32_e32 v63, v0
	v_mov_b32_e32 v112, v0
	v_mov_b32_e32 v113, v0
	v_mov_b32_e32 v114, v0
	v_mov_b32_e32 v115, v0
	v_mov_b32_e32 v116, v0
	v_mov_b32_e32 v117, v0
	v_mov_b32_e32 v118, v0
	v_mov_b32_e32 v119, v0
	v_mov_b32_e32 v120, v0
	v_mov_b32_e32 v121, v0
	v_mov_b32_e32 v122, v0
	v_mov_b32_e32 v123, v0
	v_mov_b32_e32 v124, v0
	v_mov_b32_e32 v125, v0
	v_mov_b32_e32 v126, v0
	v_mov_b32_e32 v127, v0
	s_barrier
	v_readfirstlane_b32 s82, v223
	s_and_b32 s81, s80, 0x10000
	v_add_u32_e32 v237, s81, v231
	v_add_u32_e32 v236, s81, v228
	s_xor_b32 s81, s81, 0x10000
	s_add_i32 s81, s81, s82
	v_add_u32_e32 v238, v237, v227
	v_add_u32_e32 v239, v236, v227
	ds_read_b128 v[164:167], v238 offset:32768
	ds_read_b128 v[172:175], v239
	ds_read_b128 v[156:159], v238 offset:36864
	ds_read_b128 v[168:171], v239 offset:4096
	ds_read_b128 v[160:163], v239 offset:8192
	ds_read_b128 v[152:155], v239 offset:12288
	s_mov_b32 m0, s81
	v_lshl_add_u64 v[240:241], v[204:205], 0, s[52:53]
	global_load_lds_dwordx4 v[240:241], off
	s_add_u32 m0, s81, 0x2000
	v_lshl_add_u64 v[242:243], v[206:207], 0, s[52:53]
	global_load_lds_dwordx4 v[242:243], off
	s_add_u32 m0, s81, 0x4000
	v_lshl_add_u64 v[240:241], v[208:209], 0, s[52:53]
	global_load_lds_dwordx4 v[240:241], off
	s_add_u32 m0, s81, 0x6000
	v_lshl_add_u64 v[242:243], v[210:211], 0, s[52:53]
	global_load_lds_dwordx4 v[242:243], off
	s_add_u32 m0, s81, 0x8000
	v_lshl_add_u64 v[240:241], v[212:213], 0, s[52:53]
	global_load_lds_dwordx4 v[240:241], off
	s_add_u32 m0, s81, 0xa000
	v_lshl_add_u64 v[242:243], v[214:215], 0, s[52:53]
	global_load_lds_dwordx4 v[242:243], off
	s_add_u32 m0, s81, 0xc000
	v_lshl_add_u64 v[240:241], v[216:217], 0, s[52:53]
	global_load_lds_dwordx4 v[240:241], off
	s_add_u32 m0, s81, 0xe000
	v_lshl_add_u64 v[242:243], v[218:219], 0, s[52:53]
	global_load_lds_dwordx4 v[242:243], off
	s_branch .Lp9_g0
; DI void wait_vm0() { asm volatile("s_waitcnt vmcnt(0)" ::: "memory"); }
; DI void bar_() { __builtin_amdgcn_s_barrier(); }
; #define GLDS(gp, lp) __builtin_amdgcn_global_load_lds((const unsigned*)(gp), (__attribute__((address_space(3))) unsigned*)(lp), 16, 0, 0)
; #define SB_ __builtin_amdgcn_sched_barrier(0)
; #define LOADF(A_, B_, ks) do { const int po_ = (((ks) * 2 + hh) ^ sw) * 16; \
;       _Pragma("unroll") for (int tm = 0; tm < TM; ++tm) A_[tm] = *(const bf16x8*)(As + tm * 32 * LDR + po_); \
;       _Pragma("unroll") for (int tn = 0; tn < TN; ++tn) B_[tn] = *(const bf16x8*)(Bs + tn * 32 * LDR + po_); } while (0)
; template <int TM, int TN, int WM, int WN, bool SUMSQ, int NST, class AF, class BF, class AFN, class BFN>
; DI void gemm8x(f32x16 (&acc)[TM][TN], AF arow, BF brow, int K, char* smem, float& sumsq, bool pre, bool hasNext, AFN arowN, BFN browN) {
;     ...
;   auto compute = [&](const char* cur, char* nxt, bool issue, const bf16_t* q0, const bf16_t* q1, const bf16_t* q2, const bf16_t* q3,
;                      const bf16_t* s0, const bf16_t* s1, const bf16_t* s2, const bf16_t* s3) {
;     const char* As = cur + aoff;
;     const char* Bs = cur + boff;
;     char* l_ = nxt + t * 16; char* m_ = l_ + RA * LDR;
;     bf16x8 a0[TM], b0[TN], a1[TM], b1[TN];
;     ...
;     LOADF(a0, b0, 0);
;     LOADF(a1, b1, 1);
;     SB_;
;     if (issue) { if (a0v) GLDS(q0, l_); if (a1v) GLDS(q1, l_ + 8192); }
;     SB_;
;     __builtin_amdgcn_s_setprio(1);
;     MMF(a0, b0);
;     LOADF(a0, b0, 2);
;     SB_;
;     if (issue) { if (a2v) GLDS(q2, l_ + 16384); if (a3v) GLDS(q3, l_ + 24576); }
;     SB_;
;     MMF(a1, b1);
;     LOADF(a1, b1, 3);
;     SB_;
;     if (issue) { if (b0v) GLDS(s0, m_); if (b1v) GLDS(s1, m_ + 8192); }
;     SB_;
;     MMF(a0, b0);
;     SB_;
;     if (issue) { if (b2v) GLDS(s2, m_ + 16384); if (b3v) GLDS(s3, m_ + 24576); }
;     SB_;
;     MMF(a1, b1);
;     __builtin_amdgcn_s_setprio(0);
;   };
;   int sc_ = 0;
;   for (int kt = 0; kt < nk - 1; ++kt) {
;     SB_;
;     if (NST == 2) {
;       const int ko = (kt + 1) * 64;
;       compute(smem + (kt & 1) * STAGE, smem + ((kt + 1) & 1) * STAGE, true, pa0 + ko, pa1 + ko, pa2 + ko, pa3 + ko, pb0 + ko, pb1 + ko, pb2 + ko, pb3 + ko);
;       SB_;
;       wait_vm0(); bar_();
.Lp9_loop:
	s_and_b32 s81, s80, 0x10000
	v_add_u32_e32 v237, s81, v231
	v_add_u32_e32 v236, s81, v228
	s_xor_b32 s81, s81, 0x10000
	s_add_i32 s81, s81, s82
	v_add_u32_e32 v238, v237, v227
	v_add_u32_e32 v239, v236, v227
	s_setprio 1
	v_mfma_f32_32x32x16_bf16 v[112:127], v[148:151], v[140:143], v[112:127]
	ds_read_b128 v[164:167], v238 offset:32768
	ds_read_b128 v[172:175], v239
	s_mov_b32 m0, s81
	v_lshl_add_u64 v[240:241], v[204:205], 0, s[52:53]
	global_load_lds_dwordx4 v[240:241], off
	v_mfma_f32_32x32x16_bf16 v[48:63], v[148:151], v[132:135], v[48:63]
	ds_read_b128 v[156:159], v238 offset:36864
	ds_read_b128 v[168:171], v239 offset:4096
	s_add_u32 m0, s81, 0x2000
	v_lshl_add_u64 v[242:243], v[206:207], 0, s[52:53]
	global_load_lds_dwordx4 v[242:243], off
	v_mfma_f32_32x32x16_bf16 v[96:111], v[144:147], v[140:143], v[96:111]
	ds_read_b128 v[160:163], v239 offset:8192
	s_add_u32 m0, s81, 0x4000
	v_lshl_add_u64 v[240:241], v[208:209], 0, s[52:53]
	global_load_lds_dwordx4 v[240:241], off
	v_mfma_f32_32x32x16_bf16 v[32:47], v[144:147], v[132:135], v[32:47]
	ds_read_b128 v[152:155], v239 offset:12288
	s_add_u32 m0, s81, 0x6000
	v_lshl_add_u64 v[242:243], v[210:211], 0, s[52:53]
	global_load_lds_dwordx4 v[242:243], off
	v_mfma_f32_32x32x16_bf16 v[80:95], v[136:139], v[140:143], v[80:95]
	s_add_u32 m0, s81, 0x8000
	v_lshl_add_u64 v[240:241], v[212:213], 0, s[52:53]
	global_load_lds_dwordx4 v[240:241], off
	v_mfma_f32_32x32x16_bf16 v[16:31], v[136:139], v[132:135], v[16:31]
	s_add_u32 m0, s81, 0xa000
	v_lshl_add_u64 v[242:243], v[214:215], 0, s[52:53]
	global_load_lds_dwordx4 v[242:243], off
	v_mfma_f32_32x32x16_bf16 v[64:79], v[128:131], v[140:143], v[64:79]
	s_add_u32 m0, s81, 0xc000
	v_lshl_add_u64 v[240:241], v[216:217], 0, s[52:53]
	global_load_lds_dwordx4 v[240:241], off
	v_mfma_f32_32x32x16_bf16 v[0:15], v[128:131], v[132:135], v[0:15]
	s_add_u32 m0, s81, 0xe000
	v_lshl_add_u64 v[242:243], v[218:219], 0, s[52:53]
	global_load_lds_dwordx4 v[242:243], off
.Lp9_g0:
	s_setprio 1
	v_add_u32_e32 v238, v237, v226
	v_add_u32_e32 v239, v236, v226
	s_waitcnt lgkmcnt(0)
	v_mfma_f32_32x32x16_bf16 v[112:127], v[172:175], v[164:167], v[112:127]
	ds_read_b128 v[140:143], v238 offset:32768
	ds_read_b128 v[148:151], v239
	v_mfma_f32_32x32x16_bf16 v[48:63], v[172:175], v[156:159], v[48:63]
	ds_read_b128 v[132:135], v238 offset:36864
	ds_read_b128 v[144:147], v239 offset:4096
	v_mfma_f32_32x32x16_bf16 v[96:111], v[168:171], v[164:167], v[96:111]
	ds_read_b128 v[136:139], v239 offset:8192
	v_mfma_f32_32x32x16_bf16 v[32:47], v[168:171], v[156:159], v[32:47]
	ds_read_b128 v[128:131], v239 offset:12288
	v_mfma_f32_32x32x16_bf16 v[80:95], v[160:163], v[164:167], v[80:95]
	v_mfma_f32_32x32x16_bf16 v[16:31], v[160:163], v[156:159], v[16:31]
	v_mfma_f32_32x32x16_bf16 v[64:79], v[152:155], v[164:167], v[64:79]
	v_mfma_f32_32x32x16_bf16 v[0:15], v[152:155], v[156:159], v[0:15]
	v_add_u32_e32 v238, v237, v225
	v_add_u32_e32 v239, v236, v225
	s_waitcnt lgkmcnt(0)
	v_mfma_f32_32x32x16_bf16 v[112:127], v[148:151], v[140:143], v[112:127]
	ds_read_b128 v[164:167], v238 offset:32768
	ds_read_b128 v[172:175], v239
	v_mfma_f32_32x32x16_bf16 v[48:63], v[148:151], v[132:135], v[48:63]
	ds_read_b128 v[156:159], v238 offset:36864
	ds_read_b128 v[168:171], v239 offset:4096
	v_mfma_f32_32x32x16_bf16 v[96:111], v[144:147], v[140:143], v[96:111]
	ds_read_b128 v[160:163], v239 offset:8192
	v_mfma_f32_32x32x16_bf16 v[32:47], v[144:147], v[132:135], v[32:47]
	ds_read_b128 v[152:155], v239 offset:12288
	v_mfma_f32_32x32x16_bf16 v[80:95], v[136:139], v[140:143], v[80:95]
	v_mfma_f32_32x32x16_bf16 v[16:31], v[136:139], v[132:135], v[16:31]
	v_mfma_f32_32x32x16_bf16 v[64:79], v[128:131], v[140:143], v[64:79]
	v_mfma_f32_32x32x16_bf16 v[0:15], v[128:131], v[132:135], v[0:15]
	v_add_u32_e32 v238, v237, v224
	v_add_u32_e32 v239, v236, v224
	s_waitcnt lgkmcnt(0)
	v_mfma_f32_32x32x16_bf16 v[112:127], v[172:175], v[164:167], v[112:127]
	ds_read_b128 v[140:143], v238 offset:32768
	ds_read_b128 v[148:151], v239
	v_mfma_f32_32x32x16_bf16 v[48:63], v[172:175], v[156:159], v[48:63]
	ds_read_b128 v[132:135], v238 offset:36864
	ds_read_b128 v[144:147], v239 offset:4096
	v_mfma_f32_32x32x16_bf16 v[96:111], v[168:171], v[164:167], v[96:111]
	ds_read_b128 v[136:139], v239 offset:8192
	v_mfma_f32_32x32x16_bf16 v[32:47], v[168:171], v[156:159], v[32:47]
	ds_read_b128 v[128:131], v239 offset:12288
	v_mfma_f32_32x32x16_bf16 v[80:95], v[160:163], v[164:167], v[80:95]
	v_mfma_f32_32x32x16_bf16 v[16:31], v[160:163], v[156:159], v[16:31]
	v_mfma_f32_32x32x16_bf16 v[64:79], v[152:155], v[164:167], v[64:79]
	v_mfma_f32_32x32x16_bf16 v[0:15], v[152:155], v[156:159], v[0:15]
	s_setprio 0
	s_waitcnt vmcnt(0) lgkmcnt(0)
	s_add_i32 s80, s80, 0x10000
	s_add_u32 s52, s52, 0x80
	s_addc_u32 s53, s53, 0
	s_cmpk_eq_i32 s52, 0x780
	s_barrier
	s_cbranch_scc0 .Lp9_loop
; DI void lds_sync() { wait_lgkm0(); bar_(); }
; #define SB_ __builtin_amdgcn_sched_barrier(0)
; template <int TM, int TN, int WM, int WN, bool SUMSQ, int NST, class AF, class BF, class AFN, class BFN>
; DI void gemm8x(f32x16 (&acc)[TM][TN], AF arow, BF brow, int K, char* smem, float& sumsq, bool pre, bool hasNext, AFN arowN, BFN browN) {
;     ...
;     const bf16_t *q0 = pa0, *q1 = pa0, *q2 = pa0, *q3 = pa0, *s0 = pa0, *s1 = pa0, *s2 = pa0, *s3 = pa0;
;     if (hasNext) {
;       q0 = arowN(a0v ? row0 : 0) + c * 8; q1 = arowN(a1v ? row0 + 64 : 0) + c * 8; q2 = arowN(a2v ? row0 + 128 : 0) + c * 8; q3 = arowN(a3v ? row0 + 192 : 0) + c * 8;
;       s0 = browN(b0v ? row0 : 0) + c * 8; s1 = browN(b1v ? row0 + 64 : 0) + c * 8; s2 = browN(b2v ? row0 + 128 : 0) + c * 8; s3 = browN(b3v ? row0 + 192 : 0) + c * 8;
;     }
;     SB_;
;     compute(smem + ((nk - 1) & 1) * STAGE, smem, hasNext, q0, q1, q2, q3, s0, s1, s2, s3);
;     SB_;
;     lds_sync();
; DI void phase9_10(const Params& p, char* smem) {
;     ...
;     for (int ft = 0; ft < 4; ++ft) {
;       const bool hasNext = ft < 3;
;       const bf16_t* Ab = p.WguT + ((size_t)e * 1024 + ft * 256) * DM;
;       const bf16_t* AbN = Ab + (size_t)256 * DM;
;       f32x16 acc[4][2];
; #pragma unroll
;       for (int a = 0; a < 4; ++a)
; #pragma unroll
;         for (int c = 0; c < 2; ++c) acc[a][c] = zero16();
;       float dummy = 0.f;
;       gemm8x<4, 2, 2, 4, false, 2>(acc, [&](int row) { return Ab + (size_t)row * DM; }, [&](int row) { return hb + (size_t)ib[row] * DM; }, DM, smem, dummy,
;                                    pre, hasNext, [&](int row) { return AbN + (size_t)row * DM; }, [&](int row) { return hb + (size_t)ib[row] * DM; });
;       pre = hasNext;
	s_and_b32 s81, s80, 0x10000
	v_add_u32_e32 v237, s81, v231
	v_add_u32_e32 v236, s81, v228
	s_xor_b32 s81, s81, 0x10000
	s_add_i32 s81, s81, s82
	v_add_u32_e32 v238, v237, v227
	v_add_u32_e32 v239, v236, v227
	s_setprio 1
	v_mfma_f32_32x32x16_bf16 v[112:127], v[148:151], v[140:143], v[112:127]
	ds_read_b128 v[164:167], v238 offset:32768
	ds_read_b128 v[172:175], v239
	v_mfma_f32_32x32x16_bf16 v[48:63], v[148:151], v[132:135], v[48:63]
	ds_read_b128 v[156:159], v238 offset:36864
	ds_read_b128 v[168:171], v239 offset:4096
	v_mfma_f32_32x32x16_bf16 v[96:111], v[144:147], v[140:143], v[96:111]
	ds_read_b128 v[160:163], v239 offset:8192
	v_mfma_f32_32x32x16_bf16 v[32:47], v[144:147], v[132:135], v[32:47]
	ds_read_b128 v[152:155], v239 offset:12288
	v_mfma_f32_32x32x16_bf16 v[80:95], v[136:139], v[140:143], v[80:95]
	v_mfma_f32_32x32x16_bf16 v[16:31], v[136:139], v[132:135], v[16:31]
	v_mfma_f32_32x32x16_bf16 v[64:79], v[128:131], v[140:143], v[64:79]
	v_mfma_f32_32x32x16_bf16 v[0:15], v[128:131], v[132:135], v[0:15]
	s_setprio 1
	v_add_u32_e32 v238, v237, v226
	v_add_u32_e32 v239, v236, v226
	s_waitcnt lgkmcnt(0)
	v_mfma_f32_32x32x16_bf16 v[112:127], v[172:175], v[164:167], v[112:127]
	ds_read_b128 v[140:143], v238 offset:32768
	ds_read_b128 v[148:151], v239
	v_mfma_f32_32x32x16_bf16 v[48:63], v[172:175], v[156:159], v[48:63]
	ds_read_b128 v[132:135], v238 offset:36864
	ds_read_b128 v[144:147], v239 offset:4096
	v_mfma_f32_32x32x16_bf16 v[96:111], v[168:171], v[164:167], v[96:111]
	ds_read_b128 v[136:139], v239 offset:8192
	v_mfma_f32_32x32x16_bf16 v[32:47], v[168:171], v[156:159], v[32:47]
	ds_read_b128 v[128:131], v239 offset:12288
	v_mfma_f32_32x32x16_bf16 v[80:95], v[160:163], v[164:167], v[80:95]
	v_mfma_f32_32x32x16_bf16 v[16:31], v[160:163], v[156:159], v[16:31]
	v_mfma_f32_32x32x16_bf16 v[64:79], v[152:155], v[164:167], v[64:79]
	v_mfma_f32_32x32x16_bf16 v[0:15], v[152:155], v[156:159], v[0:15]
	v_add_u32_e32 v238, v237, v225
	v_add_u32_e32 v239, v236, v225
	s_waitcnt lgkmcnt(0)
	v_mfma_f32_32x32x16_bf16 v[112:127], v[148:151], v[140:143], v[112:127]
	ds_read_b128 v[164:167], v238 offset:32768
	ds_read_b128 v[172:175], v239
	v_mfma_f32_32x32x16_bf16 v[48:63], v[148:151], v[132:135], v[48:63]
	ds_read_b128 v[156:159], v238 offset:36864
	ds_read_b128 v[168:171], v239 offset:4096
	v_mfma_f32_32x32x16_bf16 v[96:111], v[144:147], v[140:143], v[96:111]
	ds_read_b128 v[160:163], v239 offset:8192
	v_mfma_f32_32x32x16_bf16 v[32:47], v[144:147], v[132:135], v[32:47]
	ds_read_b128 v[152:155], v239 offset:12288
	v_mfma_f32_32x32x16_bf16 v[80:95], v[136:139], v[140:143], v[80:95]
	v_mfma_f32_32x32x16_bf16 v[16:31], v[136:139], v[132:135], v[16:31]
	v_mfma_f32_32x32x16_bf16 v[64:79], v[128:131], v[140:143], v[64:79]
	v_mfma_f32_32x32x16_bf16 v[0:15], v[128:131], v[132:135], v[0:15]
	v_add_u32_e32 v238, v237, v224
	v_add_u32_e32 v239, v236, v224
	s_waitcnt lgkmcnt(0)
	v_mfma_f32_32x32x16_bf16 v[112:127], v[172:175], v[164:167], v[112:127]
	ds_read_b128 v[140:143], v238 offset:32768
	ds_read_b128 v[148:151], v239
	v_mfma_f32_32x32x16_bf16 v[48:63], v[172:175], v[156:159], v[48:63]
	ds_read_b128 v[132:135], v238 offset:36864
	ds_read_b128 v[144:147], v239 offset:4096
	v_mfma_f32_32x32x16_bf16 v[96:111], v[168:171], v[164:167], v[96:111]
	ds_read_b128 v[136:139], v239 offset:8192
	v_mfma_f32_32x32x16_bf16 v[32:47], v[168:171], v[156:159], v[32:47]
	ds_read_b128 v[128:131], v239 offset:12288
	v_mfma_f32_32x32x16_bf16 v[80:95], v[160:163], v[164:167], v[80:95]
	v_mfma_f32_32x32x16_bf16 v[16:31], v[160:163], v[156:159], v[16:31]
	v_mfma_f32_32x32x16_bf16 v[64:79], v[152:155], v[164:167], v[64:79]
	v_mfma_f32_32x32x16_bf16 v[0:15], v[152:155], v[156:159], v[0:15]
	s_waitcnt lgkmcnt(0)
	v_mfma_f32_32x32x16_bf16 v[112:127], v[148:151], v[140:143], v[112:127]
	v_mfma_f32_32x32x16_bf16 v[48:63], v[148:151], v[132:135], v[48:63]
	v_mfma_f32_32x32x16_bf16 v[96:111], v[144:147], v[140:143], v[96:111]
	v_mfma_f32_32x32x16_bf16 v[32:47], v[144:147], v[132:135], v[32:47]
	v_mfma_f32_32x32x16_bf16 v[80:95], v[136:139], v[140:143], v[80:95]
	v_mfma_f32_32x32x16_bf16 v[16:31], v[136:139], v[132:135], v[16:31]
	v_mfma_f32_32x32x16_bf16 v[64:79], v[128:131], v[140:143], v[64:79]
	v_mfma_f32_32x32x16_bf16 v[0:15], v[128:131], v[132:135], v[0:15]
	s_cmp_lg_u32 s79, 3
	s_cselect_b64 s[52:53], -1, 0
	s_cbranch_scc0 .Lp9_nonext
	global_load_dword v128, v[194:195], off
	global_load_dword v130, v[192:193], off
	global_load_dword v132, v[190:191], off
	global_load_dword v134, v[188:189], off
	s_add_u32 s12, s12, 0x80000
	s_addc_u32 s13, s13, 0
	v_lshl_add_u64 v[136:137], s[12:13], 0, v[196:197]
	v_lshl_add_u64 v[138:139], s[12:13], 0, v[198:199]
	v_lshl_add_u64 v[140:141], s[12:13], 0, v[200:201]
	v_lshl_add_u64 v[142:143], s[12:13], 0, v[202:203]
	v_lshl_add_u64 v[186:187], v[136:137], 0, v[184:185]
	v_lshl_add_u64 v[164:165], v[138:139], 0, v[184:185]
	v_lshl_add_u64 v[214:215], v[140:141], 0, v[184:185]
	v_lshl_add_u64 v[212:213], v[142:143], 0, v[184:185]
	s_waitcnt vmcnt(0)
	v_ashrrev_i32_e32 v129, 31, v128
	v_ashrrev_i32_e32 v131, 31, v130
	v_ashrrev_i32_e32 v133, 31, v132
	v_ashrrev_i32_e32 v135, 31, v134
	v_lshlrev_b64 v[128:129], 11, v[128:129]
	v_lshlrev_b64 v[130:131], 11, v[130:131]
	v_lshlrev_b64 v[132:133], 11, v[132:133]
	v_lshlrev_b64 v[134:135], 11, v[134:135]
	v_lshl_add_u64 v[128:129], s[48:49], 0, v[128:129]
	v_lshl_add_u64 v[130:131], s[48:49], 0, v[130:131]
	v_lshl_add_u64 v[132:133], s[48:49], 0, v[132:133]
	v_lshl_add_u64 v[134:135], s[48:49], 0, v[134:135]
	v_lshl_add_u64 v[210:211], v[128:129], 0, v[184:185]
	v_lshl_add_u64 v[208:209], v[130:131], 0, v[184:185]
	v_lshl_add_u64 v[206:207], v[132:133], 0, v[184:185]
	v_lshl_add_u64 v[204:205], v[134:135], 0, v[184:185]
	s_mov_b32 m0, s82
	s_nop 0
	global_load_lds_dwordx4 v[186:187], off
	s_add_u32 m0, s82, 0x2000
	s_nop 0
	global_load_lds_dwordx4 v[164:165], off
	s_add_u32 m0, s82, 0x4000
	s_nop 0
	global_load_lds_dwordx4 v[214:215], off
	s_add_u32 m0, s82, 0x6000
	s_nop 0
	global_load_lds_dwordx4 v[212:213], off
	s_add_u32 m0, s82, 0x8000
	s_nop 0
	global_load_lds_dwordx4 v[210:211], off
	s_add_u32 m0, s82, 0xa000
	s_nop 0
	global_load_lds_dwordx4 v[208:209], off
	s_add_u32 m0, s82, 0xc000
	s_nop 0
	global_load_lds_dwordx4 v[206:207], off
	s_add_u32 m0, s82, 0xe000
	s_nop 0
	global_load_lds_dwordx4 v[204:205], off
; DI unsigned pk_bf16(float lo, float hi) { f32x2v v = {lo, hi}; bf16x2v b = __builtin_convertvector(v, bf16x2v); return __builtin_bit_cast(unsigned, b); }
; DI float sigmoidf_(float x) { return 1.f / (1.f + __expf(-x)); }
; DI void phase9_10(const Params& p, char* smem) {
;     ...
; #pragma unroll
;       for (int tn = 0; tn < 2; ++tn)
; #pragma unroll
;         for (int pr = 0; pr < 2; ++pr) {
;           char* d = tile + (wn * 64 + tn * 32 + r) * 272 + (wm * 64 + pr * 32 + 4 * hh) * 2;
; #pragma unroll
;           for (int q = 0; q < 4; ++q) {
;             float v[4];
; #pragma unroll
;             for (int j = 0; j < 4; ++j) { const float g = acc[2 * pr][tn][4 * q + j], uu = acc[2 * pr + 1][tn][4 * q + j]; v[j] = g * sigmoidf_(g) * uu; }
;             uint2 ou; ou.x = pk_bf16(v[0], v[1]); ou.y = pk_bf16(v[2], v[3]);
;             *(uint2*)(d + 16 * q) = ou;
.Lp9_nonext:
	s_setprio 0
	s_nop 4
	v_mul_f32_e32 v128, 0xbfb8aa3b, v112
	v_mul_f32_e32 v129, 0xbfb8aa3b, v113
	v_exp_f32_e32 v128, v128
	v_exp_f32_e32 v129, v129
	s_waitcnt lgkmcnt(0)
	s_barrier
	v_pk_add_f32 v[128:129], v[128:129], 1.0 op_sel_hi:[1,0]
	s_nop 0
	v_div_scale_f32 v130, s[4:5], v129, v129, 1.0
	v_rcp_f32_e32 v131, v130
	s_nop 0
	v_fma_f32 v132, -v130, v131, 1.0
	v_fmac_f32_e32 v131, v132, v131
	v_div_scale_f32 v132, vcc, 1.0, v129, 1.0
	v_mul_f32_e32 v133, v132, v131
	v_fma_f32 v134, -v130, v133, v132
	v_fmac_f32_e32 v133, v134, v131
	v_fma_f32 v130, -v130, v133, v132
	v_div_scale_f32 v132, s[4:5], v128, v128, 1.0
	v_rcp_f32_e32 v134, v132
	v_div_fmas_f32 v130, v130, v131, v133
	v_div_fixup_f32 v129, v130, v129, 1.0
	v_div_scale_f32 v133, vcc, 1.0, v128, 1.0
	v_fma_f32 v130, -v132, v134, 1.0
	v_fmac_f32_e32 v134, v130, v134
	v_mul_f32_e32 v135, v133, v134
	v_fma_f32 v130, -v132, v135, v133
	v_fmac_f32_e32 v135, v130, v134
	v_mul_f32_e32 v130, 0xbfb8aa3b, v114
	v_mul_f32_e32 v131, 0xbfb8aa3b, v115
	v_exp_f32_e32 v130, v130
	v_exp_f32_e32 v131, v131
	v_fma_f32 v132, -v132, v135, v133
	v_div_fmas_f32 v132, v132, v134, v135
	v_div_fixup_f32 v128, v132, v128, 1.0
	v_pk_add_f32 v[130:131], v[130:131], 1.0 op_sel_hi:[1,0]
	v_pk_mul_f32 v[112:113], v[112:113], v[128:129]
	v_div_scale_f32 v133, s[4:5], v131, v131, 1.0
	v_rcp_f32_e32 v134, v133
	v_pk_mul_f32 v[96:97], v[96:97], v[112:113]
	v_fma_f32 v112, -v133, v134, 1.0
	v_fmac_f32_e32 v134, v112, v134
	v_div_scale_f32 v112, vcc, 1.0, v131, 1.0
	v_mul_f32_e32 v113, v112, v134
	v_fma_f32 v128, -v133, v113, v112
	v_fmac_f32_e32 v113, v128, v134
	v_div_scale_f32 v128, s[4:5], v130, v130, 1.0
	v_rcp_f32_e32 v132, v128
	v_fma_f32 v112, -v133, v113, v112
	v_div_fmas_f32 v112, v112, v134, v113
	v_div_fixup_f32 v113, v112, v131, 1.0
	v_fma_f32 v112, -v128, v132, 1.0
	v_fmac_f32_e32 v132, v112, v132
	v_div_scale_f32 v112, vcc, 1.0, v130, 1.0
	v_mul_f32_e32 v131, v112, v132
	v_fma_f32 v129, -v128, v131, v112
	v_fmac_f32_e32 v131, v129, v132
	v_fma_f32 v112, -v128, v131, v112
	v_mul_f32_e32 v128, 0xbfb8aa3b, v116
	v_mul_f32_e32 v129, 0xbfb8aa3b, v117
	v_exp_f32_e32 v128, v128
	v_exp_f32_e32 v129, v129
	v_div_fmas_f32 v112, v112, v132, v131
	v_div_fixup_f32 v112, v112, v130, 1.0
	v_pk_mul_f32 v[112:113], v[114:115], v[112:113]
	v_pk_add_f32 v[114:115], v[128:129], 1.0 op_sel_hi:[1,0]
	v_pk_mul_f32 v[98:99], v[98:99], v[112:113]
	v_div_scale_f32 v128, s[4:5], v115, v115, 1.0
	v_rcp_f32_e32 v129, v128
	v_cvt_pk_bf16_f32 v96, v96, v97
	v_cvt_pk_bf16_f32 v97, v98, v99
	v_mul_f32_e32 v113, 0xbfb8aa3b, v119
	v_fma_f32 v98, -v128, v129, 1.0
	v_fmac_f32_e32 v129, v98, v129
	v_div_scale_f32 v98, vcc, 1.0, v115, 1.0
	v_mul_f32_e32 v99, v98, v129
	v_fma_f32 v112, -v128, v99, v98
	v_fmac_f32_e32 v99, v112, v129
	v_fma_f32 v98, -v128, v99, v98
	v_div_scale_f32 v128, s[4:5], v114, v114, 1.0
	v_rcp_f32_e32 v130, v128
	v_div_fmas_f32 v98, v98, v129, v99
	v_div_fixup_f32 v99, v98, v115, 1.0
	v_exp_f32_e32 v113, v113
	v_fma_f32 v98, -v128, v130, 1.0
	v_fmac_f32_e32 v130, v98, v130
	v_div_scale_f32 v98, vcc, 1.0, v114, 1.0
	v_mul_f32_e32 v115, v98, v130
	v_fma_f32 v112, -v128, v115, v98
	v_fmac_f32_e32 v115, v112, v130
	v_mul_f32_e32 v112, 0xbfb8aa3b, v118
	v_exp_f32_e32 v112, v112
	v_fma_f32 v98, -v128, v115, v98
	v_div_fmas_f32 v98, v98, v130, v115
	v_div_fixup_f32 v98, v98, v114, 1.0
	v_pk_add_f32 v[112:113], v[112:113], 1.0 op_sel_hi:[1,0]
	v_pk_mul_f32 v[98:99], v[116:117], v[98:99]
	v_div_scale_f32 v115, s[4:5], v113, v113, 1.0
	v_rcp_f32_e32 v128, v115
	v_pk_mul_f32 v[98:99], v[100:101], v[98:99]
	v_fma_f32 v100, -v115, v128, 1.0
	v_fmac_f32_e32 v128, v100, v128
	v_div_scale_f32 v100, vcc, 1.0, v113, 1.0
	v_mul_f32_e32 v101, v100, v128
	v_fma_f32 v114, -v115, v101, v100
	v_fmac_f32_e32 v101, v114, v128
	v_div_scale_f32 v114, s[4:5], v112, v112, 1.0
	v_fma_f32 v100, -v115, v101, v100
	v_rcp_f32_e32 v115, v114
	v_div_fmas_f32 v100, v100, v128, v101
	v_div_fixup_f32 v101, v100, v113, 1.0
	v_cvt_pk_bf16_f32 v98, v98, v99
	v_fma_f32 v100, -v114, v115, 1.0
	v_fmac_f32_e32 v115, v100, v115
	v_div_scale_f32 v100, vcc, 1.0, v112, 1.0
	v_mul_f32_e32 v113, v100, v115
	v_fma_f32 v116, -v114, v113, v100
	v_fmac_f32_e32 v113, v116, v115
	v_fma_f32 v100, -v114, v113, v100
	v_div_fmas_f32 v100, v100, v115, v113
	v_mul_f32_e32 v113, 0xbfb8aa3b, v120
	v_exp_f32_e32 v114, v113
	v_mul_f32_e32 v113, 0xbfb8aa3b, v121
	v_exp_f32_e32 v115, v113
	v_div_fixup_f32 v100, v100, v112, 1.0
	v_pk_mul_f32 v[100:101], v[118:119], v[100:101]
	s_nop 0
	v_pk_mul_f32 v[100:101], v[102:103], v[100:101]
	v_pk_add_f32 v[102:103], v[114:115], 1.0 op_sel_hi:[1,0]
	v_cvt_pk_bf16_f32 v99, v100, v101
	v_div_scale_f32 v112, s[4:5], v103, v103, 1.0
	v_rcp_f32_e32 v113, v112
	s_waitcnt vmcnt(0)
; DI unsigned pk_bf16(float lo, float hi) { f32x2v v = {lo, hi}; bf16x2v b = __builtin_convertvector(v, bf16x2v); return __builtin_bit_cast(unsigned, b); }
; DI float sigmoidf_(float x) { return 1.f / (1.f + __expf(-x)); }
; DI void phase9_10(const Params& p, char* smem) {
;     ...
;       for (int tn = 0; tn < 2; ++tn)
; #pragma unroll
;         for (int pr = 0; pr < 2; ++pr) {
;           char* d = tile + (wn * 64 + tn * 32 + r) * 272 + (wm * 64 + pr * 32 + 4 * hh) * 2;
; #pragma unroll
;           for (int q = 0; q < 4; ++q) {
;             float v[4];
; #pragma unroll
;             for (int j = 0; j < 4; ++j) { const float g = acc[2 * pr][tn][4 * q + j], uu = acc[2 * pr + 1][tn][4 * q + j]; v[j] = g * sigmoidf_(g) * uu; }
;             uint2 ou; ou.x = pk_bf16(v[0], v[1]); ou.y = pk_bf16(v[2], v[3]);
;             *(uint2*)(d + 16 * q) = ou;
;           }
	ds_write2_b64 v222, v[96:97], v[98:99] offset1:2
	v_div_scale_f32 v100, s[4:5], v102, v102, 1.0
	v_fma_f32 v96, -v112, v113, 1.0
	v_fmac_f32_e32 v113, v96, v113
	v_div_scale_f32 v96, vcc, 1.0, v103, 1.0
	v_mul_f32_e32 v97, v96, v113
	v_fma_f32 v98, -v112, v97, v96
	v_rcp_f32_e32 v101, v100
	v_fmac_f32_e32 v97, v98, v113
	v_fma_f32 v96, -v112, v97, v96
	v_div_fmas_f32 v96, v96, v113, v97
	v_div_fixup_f32 v97, v96, v103, 1.0
	v_fma_f32 v96, -v100, v101, 1.0
	v_fmac_f32_e32 v101, v96, v101
	v_div_scale_f32 v96, vcc, 1.0, v102, 1.0
	v_mul_f32_e32 v103, v96, v101
	v_fma_f32 v98, -v100, v103, v96
	v_fmac_f32_e32 v103, v98, v101
	v_mul_f32_e32 v98, 0xbfb8aa3b, v122
	v_mul_f32_e32 v99, 0xbfb8aa3b, v123
	v_exp_f32_e32 v98, v98
	v_exp_f32_e32 v99, v99
	v_fma_f32 v96, -v100, v103, v96
	v_div_fmas_f32 v96, v96, v101, v103
	v_div_fixup_f32 v96, v96, v102, 1.0
	v_pk_add_f32 v[98:99], v[98:99], 1.0 op_sel_hi:[1,0]
	v_pk_mul_f32 v[96:97], v[120:121], v[96:97]
	v_div_scale_f32 v100, s[4:5], v99, v99, 1.0
	v_rcp_f32_e32 v101, v100
	v_pk_mul_f32 v[96:97], v[104:105], v[96:97]
	v_fma_f32 v102, -v100, v101, 1.0
	v_fmac_f32_e32 v101, v102, v101
	v_div_scale_f32 v102, vcc, 1.0, v99, 1.0
	v_mul_f32_e32 v103, v102, v101
	v_fma_f32 v104, -v100, v103, v102
	v_fmac_f32_e32 v103, v104, v101
	v_fma_f32 v100, -v100, v103, v102
	v_div_scale_f32 v102, s[4:5], v98, v98, 1.0
	v_rcp_f32_e32 v104, v102
	v_div_fmas_f32 v100, v100, v101, v103
	v_div_fixup_f32 v99, v100, v99, 1.0
	v_cvt_pk_bf16_f32 v96, v96, v97
	v_fma_f32 v100, -v102, v104, 1.0
	v_fmac_f32_e32 v104, v100, v104
	v_div_scale_f32 v100, vcc, 1.0, v98, 1.0
	v_mul_f32_e32 v103, v100, v104
	v_fma_f32 v101, -v102, v103, v100
	v_fmac_f32_e32 v103, v101, v104
	v_fma_f32 v102, -v102, v103, v100
	v_mul_f32_e32 v100, 0xbfb8aa3b, v124
	v_mul_f32_e32 v101, 0xbfb8aa3b, v125
	v_exp_f32_e32 v100, v100
	v_exp_f32_e32 v101, v101
	v_div_fmas_f32 v102, v102, v104, v103
	v_div_fixup_f32 v98, v102, v98, 1.0
	v_pk_mul_f32 v[98:99], v[122:123], v[98:99]
	v_pk_add_f32 v[100:101], v[100:101], 1.0 op_sel_hi:[1,0]
	v_pk_mul_f32 v[98:99], v[106:107], v[98:99]
	v_div_scale_f32 v102, s[4:5], v101, v101, 1.0
	v_rcp_f32_e32 v103, v102
	v_cvt_pk_bf16_f32 v97, v98, v99
	v_fma_f32 v98, -v102, v103, 1.0
	v_fmac_f32_e32 v103, v98, v103
	v_div_scale_f32 v98, vcc, 1.0, v101, 1.0
	v_mul_f32_e32 v99, v98, v103
	v_fma_f32 v104, -v102, v99, v98
	v_fmac_f32_e32 v99, v104, v103
	v_div_scale_f32 v104, s[4:5], v100, v100, 1.0
	v_rcp_f32_e32 v105, v104
	v_fma_f32 v98, -v102, v99, v98
	v_div_fmas_f32 v98, v98, v103, v99
	v_div_fixup_f32 v99, v98, v101, 1.0
	v_fma_f32 v98, -v104, v105, 1.0
	v_fmac_f32_e32 v105, v98, v105
	v_div_scale_f32 v98, vcc, 1.0, v100, 1.0
	v_mul_f32_e32 v101, v98, v105
	v_fma_f32 v102, -v104, v101, v98
	v_fmac_f32_e32 v101, v102, v105
	v_mul_f32_e32 v102, 0xbfb8aa3b, v126
	v_mul_f32_e32 v103, 0xbfb8aa3b, v127
	v_exp_f32_e32 v102, v102
	v_exp_f32_e32 v103, v103
	v_fma_f32 v98, -v104, v101, v98
	v_div_fmas_f32 v98, v98, v105, v101
	v_div_fixup_f32 v98, v98, v100, 1.0
	v_pk_add_f32 v[102:103], v[102:103], 1.0 op_sel_hi:[1,0]
	v_pk_mul_f32 v[98:99], v[124:125], v[98:99]
	v_div_scale_f32 v101, s[4:5], v103, v103, 1.0
	v_rcp_f32_e32 v104, v101
	v_pk_mul_f32 v[98:99], v[108:109], v[98:99]
	v_fma_f32 v100, -v101, v104, 1.0
	v_fmac_f32_e32 v104, v100, v104
	v_div_scale_f32 v100, vcc, 1.0, v103, 1.0
	v_mul_f32_e32 v105, v100, v104
	v_fma_f32 v106, -v101, v105, v100
	v_fmac_f32_e32 v105, v106, v104
	v_div_scale_f32 v106, s[4:5], v102, v102, 1.0
	v_rcp_f32_e32 v107, v106
	v_fma_f32 v100, -v101, v105, v100
	v_div_fmas_f32 v100, v100, v104, v105
	v_div_fixup_f32 v101, v100, v103, 1.0
	v_fma_f32 v100, -v106, v107, 1.0
	v_fmac_f32_e32 v107, v100, v107
	v_div_scale_f32 v100, vcc, 1.0, v102, 1.0
	v_mul_f32_e32 v103, v100, v107
	v_fma_f32 v104, -v106, v103, v100
	v_fmac_f32_e32 v103, v104, v107
	v_fma_f32 v100, -v106, v103, v100
	v_div_fmas_f32 v100, v100, v107, v103
	v_mul_f32_e32 v103, 0xbfb8aa3b, v80
	v_exp_f32_e32 v104, v103
	v_mul_f32_e32 v103, 0xbfb8aa3b, v81
	v_exp_f32_e32 v105, v103
	v_div_fixup_f32 v100, v100, v102, 1.0
	v_pk_mul_f32 v[100:101], v[126:127], v[100:101]
	v_cvt_pk_bf16_f32 v98, v98, v99
	v_pk_add_f32 v[102:103], v[104:105], 1.0 op_sel_hi:[1,0]
	v_pk_mul_f32 v[100:101], v[110:111], v[100:101]
	v_div_scale_f32 v104, s[4:5], v103, v103, 1.0
	v_rcp_f32_e32 v105, v104
	v_cvt_pk_bf16_f32 v99, v100, v101
	ds_write2_b64 v222, v[96:97], v[98:99] offset0:4 offset1:6
	v_div_scale_f32 v100, s[4:5], v102, v102, 1.0
	v_fma_f32 v96, -v104, v105, 1.0
	v_fmac_f32_e32 v105, v96, v105
	v_div_scale_f32 v96, vcc, 1.0, v103, 1.0
	v_mul_f32_e32 v97, v96, v105
	v_fma_f32 v98, -v104, v97, v96
	v_rcp_f32_e32 v101, v100
	v_fmac_f32_e32 v97, v98, v105
	v_fma_f32 v96, -v104, v97, v96
	v_div_fmas_f32 v96, v96, v105, v97
	v_div_fixup_f32 v97, v96, v103, 1.0
	v_fma_f32 v96, -v100, v101, 1.0
	v_fmac_f32_e32 v101, v96, v101
	v_div_scale_f32 v96, vcc, 1.0, v102, 1.0
	v_mul_f32_e32 v103, v96, v101
	v_fma_f32 v98, -v100, v103, v96
	v_fmac_f32_e32 v103, v98, v101
	v_mul_f32_e32 v98, 0xbfb8aa3b, v82
	v_mul_f32_e32 v99, 0xbfb8aa3b, v83
	v_exp_f32_e32 v98, v98
	v_exp_f32_e32 v99, v99
	v_fma_f32 v96, -v100, v103, v96
	v_div_fmas_f32 v96, v96, v101, v103
	v_div_fixup_f32 v96, v96, v102, 1.0
	v_pk_add_f32 v[98:99], v[98:99], 1.0 op_sel_hi:[1,0]
	v_pk_mul_f32 v[80:81], v[80:81], v[96:97]
	v_div_scale_f32 v100, s[4:5], v99, v99, 1.0
	v_rcp_f32_e32 v101, v100
	v_pk_mul_f32 v[64:65], v[64:65], v[80:81]
	v_fma_f32 v80, -v100, v101, 1.0
	v_fmac_f32_e32 v101, v80, v101
	v_div_scale_f32 v80, vcc, 1.0, v99, 1.0
	v_mul_f32_e32 v81, v80, v101
	v_fma_f32 v96, -v100, v81, v80
; DI unsigned pk_bf16(float lo, float hi) { f32x2v v = {lo, hi}; bf16x2v b = __builtin_convertvector(v, bf16x2v); return __builtin_bit_cast(unsigned, b); }
; DI float sigmoidf_(float x) { return 1.f / (1.f + __expf(-x)); }
; DI void phase9_10(const Params& p, char* smem) {
;     ...
;       for (int tn = 0; tn < 2; ++tn)
; #pragma unroll
;         for (int pr = 0; pr < 2; ++pr) {
;           char* d = tile + (wn * 64 + tn * 32 + r) * 272 + (wm * 64 + pr * 32 + 4 * hh) * 2;
; #pragma unroll
;           for (int q = 0; q < 4; ++q) {
;             float v[4];
; #pragma unroll
;             for (int j = 0; j < 4; ++j) { const float g = acc[2 * pr][tn][4 * q + j], uu = acc[2 * pr + 1][tn][4 * q + j]; v[j] = g * sigmoidf_(g) * uu; }
;             uint2 ou; ou.x = pk_bf16(v[0], v[1]); ou.y = pk_bf16(v[2], v[3]);
;             *(uint2*)(d + 16 * q) = ou;
;           }
	v_fmac_f32_e32 v81, v96, v101
	v_div_scale_f32 v96, s[4:5], v98, v98, 1.0
	v_fma_f32 v80, -v100, v81, v80
	v_rcp_f32_e32 v100, v96
	v_div_fmas_f32 v80, v80, v101, v81
	v_div_fixup_f32 v81, v80, v99, 1.0
	v_cvt_pk_bf16_f32 v64, v64, v65
	v_fma_f32 v80, -v96, v100, 1.0
	v_fmac_f32_e32 v100, v80, v100
	v_div_scale_f32 v80, vcc, 1.0, v98, 1.0
	v_mul_f32_e32 v99, v80, v100
	v_fma_f32 v97, -v96, v99, v80
	v_fmac_f32_e32 v99, v97, v100
	v_fma_f32 v80, -v96, v99, v80
	v_mul_f32_e32 v96, 0xbfb8aa3b, v84
	v_mul_f32_e32 v97, 0xbfb8aa3b, v85
	v_exp_f32_e32 v96, v96
	v_exp_f32_e32 v97, v97
	v_div_fmas_f32 v80, v80, v100, v99
	v_div_fixup_f32 v80, v80, v98, 1.0
	v_pk_mul_f32 v[80:81], v[82:83], v[80:81]
	v_pk_add_f32 v[82:83], v[96:97], 1.0 op_sel_hi:[1,0]
	v_pk_mul_f32 v[66:67], v[66:67], v[80:81]
	v_div_scale_f32 v96, s[4:5], v83, v83, 1.0
	v_rcp_f32_e32 v97, v96
	v_cvt_pk_bf16_f32 v65, v66, v67
	v_mul_f32_e32 v81, 0xbfb8aa3b, v87
	v_exp_f32_e32 v81, v81
	v_fma_f32 v66, -v96, v97, 1.0
	v_fmac_f32_e32 v97, v66, v97
	v_div_scale_f32 v66, vcc, 1.0, v83, 1.0
	v_mul_f32_e32 v67, v66, v97
	v_fma_f32 v80, -v96, v67, v66
	v_fmac_f32_e32 v67, v80, v97
	v_fma_f32 v66, -v96, v67, v66
	v_div_scale_f32 v96, s[4:5], v82, v82, 1.0
	v_rcp_f32_e32 v98, v96
	v_div_fmas_f32 v66, v66, v97, v67
	v_div_fixup_f32 v67, v66, v83, 1.0
	v_fma_f32 v66, -v96, v98, 1.0
	v_fmac_f32_e32 v98, v66, v98
	v_div_scale_f32 v66, vcc, 1.0, v82, 1.0
	v_mul_f32_e32 v83, v66, v98
	v_fma_f32 v80, -v96, v83, v66
	v_fmac_f32_e32 v83, v80, v98
	v_mul_f32_e32 v80, 0xbfb8aa3b, v86
	v_exp_f32_e32 v80, v80
	v_fma_f32 v66, -v96, v83, v66
	v_div_fmas_f32 v66, v66, v98, v83
	v_div_fixup_f32 v66, v66, v82, 1.0
	v_pk_add_f32 v[80:81], v[80:81], 1.0 op_sel_hi:[1,0]
	v_pk_mul_f32 v[66:67], v[84:85], v[66:67]
	v_div_scale_f32 v83, s[4:5], v81, v81, 1.0
	v_rcp_f32_e32 v96, v83
	v_pk_mul_f32 v[66:67], v[68:69], v[66:67]
	v_fma_f32 v68, -v83, v96, 1.0
	v_fmac_f32_e32 v96, v68, v96
	v_div_scale_f32 v68, vcc, 1.0, v81, 1.0
	v_mul_f32_e32 v69, v68, v96
	v_fma_f32 v82, -v83, v69, v68
	v_fmac_f32_e32 v69, v82, v96
	v_div_scale_f32 v82, s[4:5], v80, v80, 1.0
	v_fma_f32 v68, -v83, v69, v68
	v_rcp_f32_e32 v83, v82
	v_div_fmas_f32 v68, v68, v96, v69
	v_div_fixup_f32 v69, v68, v81, 1.0
	v_cvt_pk_bf16_f32 v66, v66, v67
	v_fma_f32 v68, -v82, v83, 1.0
	v_fmac_f32_e32 v83, v68, v83
	v_div_scale_f32 v68, vcc, 1.0, v80, 1.0
	v_mul_f32_e32 v81, v68, v83
	v_fma_f32 v84, -v82, v81, v68
	v_fmac_f32_e32 v81, v84, v83
	v_fma_f32 v68, -v82, v81, v68
	v_div_fmas_f32 v68, v68, v83, v81
	v_mul_f32_e32 v81, 0xbfb8aa3b, v88
	v_exp_f32_e32 v82, v81
	v_mul_f32_e32 v81, 0xbfb8aa3b, v89
	v_exp_f32_e32 v83, v81
	v_div_fixup_f32 v68, v68, v80, 1.0
	v_pk_mul_f32 v[68:69], v[86:87], v[68:69]
	s_nop 0
	v_pk_mul_f32 v[68:69], v[70:71], v[68:69]
	v_pk_add_f32 v[70:71], v[82:83], 1.0 op_sel_hi:[1,0]
	v_cvt_pk_bf16_f32 v67, v68, v69
	v_div_scale_f32 v80, s[4:5], v71, v71, 1.0
	v_rcp_f32_e32 v81, v80
	ds_write2_b64 v222, v[64:65], v[66:67] offset0:8 offset1:10
	v_div_scale_f32 v68, s[4:5], v70, v70, 1.0
	v_fma_f32 v64, -v80, v81, 1.0
	v_fmac_f32_e32 v81, v64, v81
	v_div_scale_f32 v64, vcc, 1.0, v71, 1.0
	v_mul_f32_e32 v65, v64, v81
	v_fma_f32 v66, -v80, v65, v64
	v_rcp_f32_e32 v69, v68
	v_fmac_f32_e32 v65, v66, v81
	v_fma_f32 v64, -v80, v65, v64
	v_div_fmas_f32 v64, v64, v81, v65
	v_div_fixup_f32 v65, v64, v71, 1.0
	v_fma_f32 v64, -v68, v69, 1.0
	v_fmac_f32_e32 v69, v64, v69
	v_div_scale_f32 v64, vcc, 1.0, v70, 1.0
	v_mul_f32_e32 v71, v64, v69
	v_fma_f32 v66, -v68, v71, v64
	v_fmac_f32_e32 v71, v66, v69
	v_mul_f32_e32 v66, 0xbfb8aa3b, v90
	v_mul_f32_e32 v67, 0xbfb8aa3b, v91
	v_exp_f32_e32 v66, v66
	v_exp_f32_e32 v67, v67
	v_fma_f32 v64, -v68, v71, v64
	v_div_fmas_f32 v64, v64, v69, v71
	v_div_fixup_f32 v64, v64, v70, 1.0
	v_pk_add_f32 v[66:67], v[66:67], 1.0 op_sel_hi:[1,0]
	v_pk_mul_f32 v[64:65], v[88:89], v[64:65]
	v_div_scale_f32 v68, s[4:5], v67, v67, 1.0
	v_rcp_f32_e32 v69, v68
	v_pk_mul_f32 v[64:65], v[72:73], v[64:65]
	v_fma_f32 v70, -v68, v69, 1.0
	v_fmac_f32_e32 v69, v70, v69
	v_div_scale_f32 v70, vcc, 1.0, v67, 1.0
	v_mul_f32_e32 v71, v70, v69
	v_fma_f32 v72, -v68, v71, v70
	v_fmac_f32_e32 v71, v72, v69
	v_fma_f32 v68, -v68, v71, v70
	v_div_scale_f32 v70, s[4:5], v66, v66, 1.0
	v_rcp_f32_e32 v72, v70
	v_div_fmas_f32 v68, v68, v69, v71
	v_div_fixup_f32 v67, v68, v67, 1.0
	v_cvt_pk_bf16_f32 v64, v64, v65
	v_fma_f32 v68, -v70, v72, 1.0
	v_fmac_f32_e32 v72, v68, v72
	v_div_scale_f32 v68, vcc, 1.0, v66, 1.0
	v_mul_f32_e32 v71, v68, v72
	v_fma_f32 v69, -v70, v71, v68
	v_fmac_f32_e32 v71, v69, v72
	v_fma_f32 v70, -v70, v71, v68
	v_mul_f32_e32 v68, 0xbfb8aa3b, v92
	v_mul_f32_e32 v69, 0xbfb8aa3b, v93
	v_exp_f32_e32 v68, v68
	v_exp_f32_e32 v69, v69
	v_div_fmas_f32 v70, v70, v72, v71
	v_div_fixup_f32 v66, v70, v66, 1.0
	v_pk_mul_f32 v[66:67], v[90:91], v[66:67]
	v_pk_add_f32 v[68:69], v[68:69], 1.0 op_sel_hi:[1,0]
	v_pk_mul_f32 v[66:67], v[74:75], v[66:67]
	v_div_scale_f32 v70, s[4:5], v69, v69, 1.0
	v_rcp_f32_e32 v71, v70
	v_cvt_pk_bf16_f32 v65, v66, v67
	v_fma_f32 v66, -v70, v71, 1.0
	v_fmac_f32_e32 v71, v66, v71
	v_div_scale_f32 v66, vcc, 1.0, v69, 1.0
	v_mul_f32_e32 v67, v66, v71
	v_fma_f32 v72, -v70, v67, v66
	v_fmac_f32_e32 v67, v72, v71
	v_div_scale_f32 v72, s[4:5], v68, v68, 1.0
	v_rcp_f32_e32 v73, v72
	v_fma_f32 v66, -v70, v67, v66
	v_div_fmas_f32 v66, v66, v71, v67
	v_div_fixup_f32 v67, v66, v69, 1.0
	v_fma_f32 v66, -v72, v73, 1.0
	v_fmac_f32_e32 v73, v66, v73
	v_div_scale_f32 v66, vcc, 1.0, v68, 1.0
	v_mul_f32_e32 v69, v66, v73
	v_fma_f32 v70, -v72, v69, v66
	v_fmac_f32_e32 v69, v70, v73
	v_mul_f32_e32 v70, 0xbfb8aa3b, v94
; DI unsigned pk_bf16(float lo, float hi) { f32x2v v = {lo, hi}; bf16x2v b = __builtin_convertvector(v, bf16x2v); return __builtin_bit_cast(unsigned, b); }
; DI float sigmoidf_(float x) { return 1.f / (1.f + __expf(-x)); }
; DI void phase9_10(const Params& p, char* smem) {
;     ...
;       for (int tn = 0; tn < 2; ++tn)
; #pragma unroll
;         for (int pr = 0; pr < 2; ++pr) {
;           char* d = tile + (wn * 64 + tn * 32 + r) * 272 + (wm * 64 + pr * 32 + 4 * hh) * 2;
; #pragma unroll
;           for (int q = 0; q < 4; ++q) {
;             float v[4];
; #pragma unroll
;             for (int j = 0; j < 4; ++j) { const float g = acc[2 * pr][tn][4 * q + j], uu = acc[2 * pr + 1][tn][4 * q + j]; v[j] = g * sigmoidf_(g) * uu; }
;             uint2 ou; ou.x = pk_bf16(v[0], v[1]); ou.y = pk_bf16(v[2], v[3]);
;             *(uint2*)(d + 16 * q) = ou;
;           }
	v_mul_f32_e32 v71, 0xbfb8aa3b, v95
	v_exp_f32_e32 v70, v70
	v_exp_f32_e32 v71, v71
	v_fma_f32 v66, -v72, v69, v66
	v_div_fmas_f32 v66, v66, v73, v69
	v_div_fixup_f32 v66, v66, v68, 1.0
	v_pk_add_f32 v[70:71], v[70:71], 1.0 op_sel_hi:[1,0]
	v_pk_mul_f32 v[66:67], v[92:93], v[66:67]
	v_div_scale_f32 v69, s[4:5], v71, v71, 1.0
	v_rcp_f32_e32 v72, v69
	v_pk_mul_f32 v[66:67], v[76:77], v[66:67]
	v_fma_f32 v68, -v69, v72, 1.0
	v_fmac_f32_e32 v72, v68, v72
	v_div_scale_f32 v68, vcc, 1.0, v71, 1.0
	v_mul_f32_e32 v73, v68, v72
	v_fma_f32 v74, -v69, v73, v68
	v_fmac_f32_e32 v73, v74, v72
	v_div_scale_f32 v74, s[4:5], v70, v70, 1.0
	v_rcp_f32_e32 v75, v74
	v_fma_f32 v68, -v69, v73, v68
	v_div_fmas_f32 v68, v68, v72, v73
	v_div_fixup_f32 v69, v68, v71, 1.0
	v_fma_f32 v68, -v74, v75, 1.0
	v_fmac_f32_e32 v75, v68, v75
	v_div_scale_f32 v68, vcc, 1.0, v70, 1.0
	v_mul_f32_e32 v71, v68, v75
	v_fma_f32 v72, -v74, v71, v68
	v_fmac_f32_e32 v71, v72, v75
	v_fma_f32 v68, -v74, v71, v68
	v_div_fmas_f32 v68, v68, v75, v71
	v_mul_f32_e32 v71, 0xbfb8aa3b, v48
	v_exp_f32_e32 v72, v71
	v_mul_f32_e32 v71, 0xbfb8aa3b, v49
	v_exp_f32_e32 v73, v71
	v_div_fixup_f32 v68, v68, v70, 1.0
	v_pk_mul_f32 v[68:69], v[94:95], v[68:69]
	v_cvt_pk_bf16_f32 v66, v66, v67
	v_pk_add_f32 v[70:71], v[72:73], 1.0 op_sel_hi:[1,0]
	v_pk_mul_f32 v[68:69], v[78:79], v[68:69]
	v_div_scale_f32 v72, s[4:5], v71, v71, 1.0
	v_rcp_f32_e32 v73, v72
	v_cvt_pk_bf16_f32 v67, v68, v69
	ds_write2_b64 v222, v[64:65], v[66:67] offset0:12 offset1:14
	v_div_scale_f32 v68, s[4:5], v70, v70, 1.0
	v_fma_f32 v64, -v72, v73, 1.0
	v_fmac_f32_e32 v73, v64, v73
	v_div_scale_f32 v64, vcc, 1.0, v71, 1.0
	v_mul_f32_e32 v65, v64, v73
	v_fma_f32 v66, -v72, v65, v64
	v_rcp_f32_e32 v69, v68
	v_fmac_f32_e32 v65, v66, v73
	v_fma_f32 v64, -v72, v65, v64
	v_div_fmas_f32 v64, v64, v73, v65
	v_div_fixup_f32 v65, v64, v71, 1.0
	v_fma_f32 v64, -v68, v69, 1.0
	v_fmac_f32_e32 v69, v64, v69
	v_div_scale_f32 v64, vcc, 1.0, v70, 1.0
	v_mul_f32_e32 v71, v64, v69
	v_fma_f32 v66, -v68, v71, v64
	v_fmac_f32_e32 v71, v66, v69
	v_mul_f32_e32 v66, 0xbfb8aa3b, v50
	v_mul_f32_e32 v67, 0xbfb8aa3b, v51
	v_exp_f32_e32 v66, v66
	v_exp_f32_e32 v67, v67
	v_fma_f32 v64, -v68, v71, v64
	v_div_fmas_f32 v64, v64, v69, v71
	v_div_fixup_f32 v64, v64, v70, 1.0
	v_pk_add_f32 v[66:67], v[66:67], 1.0 op_sel_hi:[1,0]
	v_pk_mul_f32 v[48:49], v[48:49], v[64:65]
	v_div_scale_f32 v68, s[4:5], v67, v67, 1.0
	v_rcp_f32_e32 v69, v68
	v_pk_mul_f32 v[32:33], v[32:33], v[48:49]
	v_fma_f32 v48, -v68, v69, 1.0
	v_fmac_f32_e32 v69, v48, v69
	v_div_scale_f32 v48, vcc, 1.0, v67, 1.0
	v_mul_f32_e32 v49, v48, v69
	v_fma_f32 v64, -v68, v49, v48
	v_fmac_f32_e32 v49, v64, v69
	v_div_scale_f32 v64, s[4:5], v66, v66, 1.0
	v_fma_f32 v48, -v68, v49, v48
	v_rcp_f32_e32 v68, v64
	v_div_fmas_f32 v48, v48, v69, v49
	v_div_fixup_f32 v49, v48, v67, 1.0
	v_fma_f32 v48, -v64, v68, 1.0
	v_fmac_f32_e32 v68, v48, v68
	v_div_scale_f32 v48, vcc, 1.0, v66, 1.0
	v_mul_f32_e32 v67, v48, v68
	v_fma_f32 v65, -v64, v67, v48
	v_fmac_f32_e32 v67, v65, v68
	v_fma_f32 v48, -v64, v67, v48
	v_mul_f32_e32 v64, 0xbfb8aa3b, v52
	v_mul_f32_e32 v65, 0xbfb8aa3b, v53
	v_exp_f32_e32 v64, v64
	v_exp_f32_e32 v65, v65
	v_div_fmas_f32 v48, v48, v68, v67
	v_div_fixup_f32 v48, v48, v66, 1.0
	v_pk_mul_f32 v[48:49], v[50:51], v[48:49]
	v_pk_add_f32 v[50:51], v[64:65], 1.0 op_sel_hi:[1,0]
	v_pk_mul_f32 v[34:35], v[34:35], v[48:49]
	v_div_scale_f32 v64, s[4:5], v51, v51, 1.0
	v_rcp_f32_e32 v65, v64
	v_cvt_pk_bf16_f32 v48, v32, v33
	v_cvt_pk_bf16_f32 v49, v34, v35
	v_mul_f32_e32 v35, 0xbfb8aa3b, v55
	v_fma_f32 v32, -v64, v65, 1.0
	v_fmac_f32_e32 v65, v32, v65
	v_div_scale_f32 v32, vcc, 1.0, v51, 1.0
	v_mul_f32_e32 v33, v32, v65
	v_fma_f32 v34, -v64, v33, v32
	v_fmac_f32_e32 v33, v34, v65
	v_fma_f32 v32, -v64, v33, v32
	v_div_scale_f32 v64, s[4:5], v50, v50, 1.0
	v_rcp_f32_e32 v66, v64
	v_div_fmas_f32 v32, v32, v65, v33
	v_div_fixup_f32 v33, v32, v51, 1.0
	v_exp_f32_e32 v35, v35
	v_fma_f32 v32, -v64, v66, 1.0
	v_fmac_f32_e32 v66, v32, v66
	v_div_scale_f32 v32, vcc, 1.0, v50, 1.0
	v_mul_f32_e32 v51, v32, v66
	v_fma_f32 v34, -v64, v51, v32
	v_fmac_f32_e32 v51, v34, v66
	v_mul_f32_e32 v34, 0xbfb8aa3b, v54
	v_exp_f32_e32 v34, v34
	v_fma_f32 v32, -v64, v51, v32
	v_div_fmas_f32 v32, v32, v66, v51
	v_div_fixup_f32 v32, v32, v50, 1.0
	v_pk_add_f32 v[34:35], v[34:35], 1.0 op_sel_hi:[1,0]
	v_pk_mul_f32 v[32:33], v[52:53], v[32:33]
	v_div_scale_f32 v51, s[4:5], v35, v35, 1.0
	v_rcp_f32_e32 v64, v51
	v_pk_mul_f32 v[32:33], v[36:37], v[32:33]
	v_fma_f32 v36, -v51, v64, 1.0
	v_fmac_f32_e32 v64, v36, v64
	v_div_scale_f32 v36, vcc, 1.0, v35, 1.0
	v_mul_f32_e32 v37, v36, v64
	v_fma_f32 v50, -v51, v37, v36
	v_fmac_f32_e32 v37, v50, v64
	v_div_scale_f32 v50, s[4:5], v34, v34, 1.0
	v_fma_f32 v36, -v51, v37, v36
	v_rcp_f32_e32 v51, v50
	v_div_fmas_f32 v36, v36, v64, v37
	v_div_fixup_f32 v35, v36, v35, 1.0
	v_fma_f32 v36, -v50, v51, 1.0
	v_fmac_f32_e32 v51, v36, v51
	v_div_scale_f32 v36, vcc, 1.0, v34, 1.0
	v_mul_f32_e32 v37, v36, v51
	v_fma_f32 v52, -v50, v37, v36
	v_fmac_f32_e32 v37, v52, v51
	v_fma_f32 v36, -v50, v37, v36
	v_div_fmas_f32 v36, v36, v51, v37
	v_div_fixup_f32 v34, v36, v34, 1.0
	v_mul_f32_e32 v36, 0xbfb8aa3b, v56
	v_mul_f32_e32 v37, 0xbfb8aa3b, v57
	v_exp_f32_e32 v36, v36
	v_exp_f32_e32 v37, v37
	v_pk_mul_f32 v[34:35], v[54:55], v[34:35]
	v_pk_add_f32 v[36:37], v[36:37], 1.0 op_sel_hi:[1,0]
	v_pk_mul_f32 v[34:35], v[38:39], v[34:35]
	v_cvt_pk_bf16_f32 v38, v32, v33
	v_div_scale_f32 v33, s[4:5], v37, v37, 1.0
	v_rcp_f32_e32 v50, v33
	v_cvt_pk_bf16_f32 v39, v34, v35
	v_add_u32_e32 v32, 0x2000, v222
	ds_write2_b64 v32, v[48:49], v[38:39] offset0:64 offset1:66
; DI unsigned pk_bf16(float lo, float hi) { f32x2v v = {lo, hi}; bf16x2v b = __builtin_convertvector(v, bf16x2v); return __builtin_bit_cast(unsigned, b); }
; DI float sigmoidf_(float x) { return 1.f / (1.f + __expf(-x)); }
; DI void phase9_10(const Params& p, char* smem) {
;     ...
;       for (int tn = 0; tn < 2; ++tn)
; #pragma unroll
;         for (int pr = 0; pr < 2; ++pr) {
;           char* d = tile + (wn * 64 + tn * 32 + r) * 272 + (wm * 64 + pr * 32 + 4 * hh) * 2;
; #pragma unroll
;           for (int q = 0; q < 4; ++q) {
;             float v[4];
; #pragma unroll
;             for (int j = 0; j < 4; ++j) { const float g = acc[2 * pr][tn][4 * q + j], uu = acc[2 * pr + 1][tn][4 * q + j]; v[j] = g * sigmoidf_(g) * uu; }
;             uint2 ou; ou.x = pk_bf16(v[0], v[1]); ou.y = pk_bf16(v[2], v[3]);
;             *(uint2*)(d + 16 * q) = ou;
;           }
	v_fma_f32 v34, -v33, v50, 1.0
	v_fmac_f32_e32 v50, v34, v50
	v_div_scale_f32 v34, vcc, 1.0, v37, 1.0
	v_mul_f32_e32 v35, v34, v50
	v_fma_f32 v38, -v33, v35, v34
	v_fmac_f32_e32 v35, v38, v50
	v_fma_f32 v33, -v33, v35, v34
	v_div_scale_f32 v34, s[4:5], v36, v36, 1.0
	v_rcp_f32_e32 v48, v34
	v_div_fmas_f32 v33, v33, v50, v35
	v_div_fixup_f32 v35, v33, v37, 1.0
	v_mul_f32_e32 v39, 0xbfb8aa3b, v59
	v_fma_f32 v33, -v34, v48, 1.0
	v_fmac_f32_e32 v48, v33, v48
	v_div_scale_f32 v33, vcc, 1.0, v36, 1.0
	v_mul_f32_e32 v37, v33, v48
	v_fma_f32 v38, -v34, v37, v33
	v_fmac_f32_e32 v37, v38, v48
	v_mul_f32_e32 v38, 0xbfb8aa3b, v58
	v_exp_f32_e32 v38, v38
	v_exp_f32_e32 v39, v39
	v_fma_f32 v33, -v34, v37, v33
	v_div_fmas_f32 v33, v33, v48, v37
	v_div_fixup_f32 v34, v33, v36, 1.0
	v_pk_add_f32 v[38:39], v[38:39], 1.0 op_sel_hi:[1,0]
	v_pk_mul_f32 v[34:35], v[56:57], v[34:35]
	v_div_scale_f32 v37, s[4:5], v39, v39, 1.0
	v_rcp_f32_e32 v48, v37
	v_pk_mul_f32 v[34:35], v[40:41], v[34:35]
	v_fma_f32 v33, -v37, v48, 1.0
	v_fmac_f32_e32 v48, v33, v48
	v_div_scale_f32 v33, vcc, 1.0, v39, 1.0
	v_mul_f32_e32 v36, v33, v48
	v_fma_f32 v40, -v37, v36, v33
	v_fmac_f32_e32 v36, v40, v48
	v_div_scale_f32 v40, s[4:5], v38, v38, 1.0
	v_rcp_f32_e32 v49, v40
	v_fma_f32 v33, -v37, v36, v33
	v_div_fmas_f32 v33, v33, v48, v36
	v_div_fixup_f32 v37, v33, v39, 1.0
	v_fma_f32 v33, -v40, v49, 1.0
	v_fmac_f32_e32 v49, v33, v49
	v_div_scale_f32 v33, vcc, 1.0, v38, 1.0
	v_mul_f32_e32 v36, v33, v49
	v_fma_f32 v39, -v40, v36, v33
	v_fmac_f32_e32 v36, v39, v49
	v_mul_f32_e32 v39, 0xbfb8aa3b, v60
	v_fma_f32 v33, -v40, v36, v33
	v_exp_f32_e32 v40, v39
	v_mul_f32_e32 v39, 0xbfb8aa3b, v61
	v_exp_f32_e32 v41, v39
	v_div_fmas_f32 v33, v33, v49, v36
	v_div_fixup_f32 v36, v33, v38, 1.0
	v_pk_mul_f32 v[36:37], v[58:59], v[36:37]
	v_pk_add_f32 v[38:39], v[40:41], 1.0 op_sel_hi:[1,0]
	v_pk_mul_f32 v[36:37], v[42:43], v[36:37]
	v_div_scale_f32 v33, s[4:5], v39, v39, 1.0
	v_rcp_f32_e32 v40, v33
	v_cvt_pk_bf16_f32 v34, v34, v35
	v_cvt_pk_bf16_f32 v35, v36, v37
	v_fma_f32 v36, -v33, v40, 1.0
	v_fmac_f32_e32 v40, v36, v40
	v_div_scale_f32 v36, vcc, 1.0, v39, 1.0
	v_mul_f32_e32 v37, v36, v40
	v_fma_f32 v41, -v33, v37, v36
	v_fmac_f32_e32 v37, v41, v40
	v_fma_f32 v33, -v33, v37, v36
	v_div_scale_f32 v36, s[4:5], v38, v38, 1.0
	v_rcp_f32_e32 v42, v36
	v_div_fmas_f32 v33, v33, v40, v37
	v_div_fixup_f32 v37, v33, v39, 1.0
	v_mul_f32_e32 v41, 0xbfb8aa3b, v63
	v_fma_f32 v33, -v36, v42, 1.0
	v_fmac_f32_e32 v42, v33, v42
	v_div_scale_f32 v33, vcc, 1.0, v38, 1.0
	v_mul_f32_e32 v39, v33, v42
	v_fma_f32 v40, -v36, v39, v33
	v_fmac_f32_e32 v39, v40, v42
	v_mul_f32_e32 v40, 0xbfb8aa3b, v62
	v_exp_f32_e32 v40, v40
	v_exp_f32_e32 v41, v41
	v_fma_f32 v33, -v36, v39, v33
	v_div_fmas_f32 v33, v33, v42, v39
	v_div_fixup_f32 v36, v33, v38, 1.0
	v_pk_add_f32 v[40:41], v[40:41], 1.0 op_sel_hi:[1,0]
	v_pk_mul_f32 v[36:37], v[60:61], v[36:37]
	v_div_scale_f32 v39, s[4:5], v41, v41, 1.0
	v_rcp_f32_e32 v42, v39
	v_pk_mul_f32 v[36:37], v[44:45], v[36:37]
	v_fma_f32 v33, -v39, v42, 1.0
	v_fmac_f32_e32 v42, v33, v42
	v_div_scale_f32 v33, vcc, 1.0, v41, 1.0
	v_mul_f32_e32 v38, v33, v42
	v_fma_f32 v43, -v39, v38, v33
	v_fmac_f32_e32 v38, v43, v42
	v_div_scale_f32 v43, s[4:5], v40, v40, 1.0
	v_rcp_f32_e32 v44, v43
	v_fma_f32 v33, -v39, v38, v33
	v_div_fmas_f32 v33, v33, v42, v38
	v_div_fixup_f32 v39, v33, v41, 1.0
	v_fma_f32 v33, -v43, v44, 1.0
	v_fmac_f32_e32 v44, v33, v44
	v_div_scale_f32 v33, vcc, 1.0, v40, 1.0
	v_mul_f32_e32 v38, v33, v44
	v_fma_f32 v41, -v43, v38, v33
	v_fmac_f32_e32 v38, v41, v44
	v_fma_f32 v33, -v43, v38, v33
	v_div_fmas_f32 v33, v33, v44, v38
	v_mul_f32_e32 v38, 0xbfb8aa3b, v16
	v_exp_f32_e32 v42, v38
	v_mul_f32_e32 v38, 0xbfb8aa3b, v17
	v_exp_f32_e32 v43, v38
	v_div_fixup_f32 v38, v33, v40, 1.0
	v_pk_mul_f32 v[38:39], v[62:63], v[38:39]
	v_cvt_pk_bf16_f32 v36, v36, v37
	v_pk_add_f32 v[40:41], v[42:43], 1.0 op_sel_hi:[1,0]
	v_pk_mul_f32 v[38:39], v[46:47], v[38:39]
	v_div_scale_f32 v33, s[4:5], v41, v41, 1.0
	v_rcp_f32_e32 v42, v33
	v_cvt_pk_bf16_f32 v37, v38, v39
	ds_write2_b64 v32, v[34:35], v[36:37] offset0:68 offset1:70
	v_mul_f32_e32 v37, 0xbfb8aa3b, v19
	v_fma_f32 v34, -v33, v42, 1.0
	v_fmac_f32_e32 v42, v34, v42
	v_div_scale_f32 v34, vcc, 1.0, v41, 1.0
	v_mul_f32_e32 v35, v34, v42
	v_fma_f32 v36, -v33, v35, v34
	v_fmac_f32_e32 v35, v36, v42
	v_fma_f32 v33, -v33, v35, v34
	v_div_scale_f32 v34, s[4:5], v40, v40, 1.0
	v_rcp_f32_e32 v38, v34
	v_div_fmas_f32 v33, v33, v42, v35
	v_div_fixup_f32 v35, v33, v41, 1.0
	v_exp_f32_e32 v37, v37
	v_fma_f32 v33, -v34, v38, 1.0
	v_fmac_f32_e32 v38, v33, v38
	v_div_scale_f32 v33, vcc, 1.0, v40, 1.0
	v_mul_f32_e32 v39, v33, v38
	v_fma_f32 v36, -v34, v39, v33
	v_fmac_f32_e32 v39, v36, v38
	v_mul_f32_e32 v36, 0xbfb8aa3b, v18
	v_exp_f32_e32 v36, v36
	v_fma_f32 v33, -v34, v39, v33
	v_div_fmas_f32 v33, v33, v38, v39
	v_div_fixup_f32 v34, v33, v40, 1.0
	v_pk_add_f32 v[36:37], v[36:37], 1.0 op_sel_hi:[1,0]
	v_pk_mul_f32 v[16:17], v[16:17], v[34:35]
	v_div_scale_f32 v38, s[4:5], v37, v37, 1.0
	v_rcp_f32_e32 v39, v38
	v_pk_mul_f32 v[0:1], v[0:1], v[16:17]
	v_fma_f32 v16, -v38, v39, 1.0
	v_fmac_f32_e32 v39, v16, v39
	v_div_scale_f32 v16, vcc, 1.0, v37, 1.0
	v_mul_f32_e32 v17, v16, v39
	v_fma_f32 v33, -v38, v17, v16
	v_fmac_f32_e32 v17, v33, v39
	v_div_scale_f32 v33, s[4:5], v36, v36, 1.0
	v_fma_f32 v16, -v38, v17, v16
	v_rcp_f32_e32 v38, v33
	v_div_fmas_f32 v16, v16, v39, v17
	v_div_fixup_f32 v17, v16, v37, 1.0
	v_cvt_pk_bf16_f32 v0, v0, v1
	v_fma_f32 v16, -v33, v38, 1.0
	v_fmac_f32_e32 v38, v16, v38
	v_div_scale_f32 v16, vcc, 1.0, v36, 1.0
	v_mul_f32_e32 v37, v16, v38
; DI unsigned pk_bf16(float lo, float hi) { f32x2v v = {lo, hi}; bf16x2v b = __builtin_convertvector(v, bf16x2v); return __builtin_bit_cast(unsigned, b); }
; DI float sigmoidf_(float x) { return 1.f / (1.f + __expf(-x)); }
; DI void lds_sync() { wait_lgkm0(); bar_(); }
; DI void phase9_10(const Params& p, char* smem) {
;     ...
;       for (int tn = 0; tn < 2; ++tn)
; #pragma unroll
;         for (int pr = 0; pr < 2; ++pr) {
;           char* d = tile + (wn * 64 + tn * 32 + r) * 272 + (wm * 64 + pr * 32 + 4 * hh) * 2;
; #pragma unroll
;           for (int q = 0; q < 4; ++q) {
;             float v[4];
; #pragma unroll
;             for (int j = 0; j < 4; ++j) { const float g = acc[2 * pr][tn][4 * q + j], uu = acc[2 * pr + 1][tn][4 * q + j]; v[j] = g * sigmoidf_(g) * uu; }
;             uint2 ou; ou.x = pk_bf16(v[0], v[1]); ou.y = pk_bf16(v[2], v[3]);
;             *(uint2*)(d + 16 * q) = ou;
;           }
;         }
;       lds_sync();
;       bf16_t* hd_ = p.hmid + (size_t)be * CAP * DE + ft * 128;
;       copy_tile(tile, 272, 256, 4, [&](int row) { return hd_ + (size_t)row * DE; }, 0, 16);
	v_fma_f32 v34, -v33, v37, v16
	v_fmac_f32_e32 v37, v34, v38
	v_fma_f32 v16, -v33, v37, v16
	v_mul_f32_e32 v33, 0xbfb8aa3b, v20
	v_exp_f32_e32 v34, v33
	v_mul_f32_e32 v33, 0xbfb8aa3b, v21
	v_exp_f32_e32 v35, v33
	v_div_fmas_f32 v16, v16, v38, v37
	v_div_fixup_f32 v16, v16, v36, 1.0
	v_pk_mul_f32 v[16:17], v[18:19], v[16:17]
	v_pk_add_f32 v[18:19], v[34:35], 1.0 op_sel_hi:[1,0]
	v_pk_mul_f32 v[2:3], v[2:3], v[16:17]
	v_div_scale_f32 v33, s[4:5], v19, v19, 1.0
	v_rcp_f32_e32 v34, v33
	v_cvt_pk_bf16_f32 v1, v2, v3
	v_mul_f32_e32 v17, 0xbfb8aa3b, v23
	v_exp_f32_e32 v17, v17
	v_fma_f32 v2, -v33, v34, 1.0
	v_fmac_f32_e32 v34, v2, v34
	v_div_scale_f32 v2, vcc, 1.0, v19, 1.0
	v_mul_f32_e32 v3, v2, v34
	v_fma_f32 v16, -v33, v3, v2
	v_fmac_f32_e32 v3, v16, v34
	v_fma_f32 v2, -v33, v3, v2
	v_div_scale_f32 v33, s[4:5], v18, v18, 1.0
	v_rcp_f32_e32 v35, v33
	v_div_fmas_f32 v2, v2, v34, v3
	v_div_fixup_f32 v3, v2, v19, 1.0
	v_fma_f32 v2, -v33, v35, 1.0
	v_fmac_f32_e32 v35, v2, v35
	v_div_scale_f32 v2, vcc, 1.0, v18, 1.0
	v_mul_f32_e32 v19, v2, v35
	v_fma_f32 v16, -v33, v19, v2
	v_fmac_f32_e32 v19, v16, v35
	v_mul_f32_e32 v16, 0xbfb8aa3b, v22
	v_exp_f32_e32 v16, v16
	v_fma_f32 v2, -v33, v19, v2
	v_div_fmas_f32 v2, v2, v35, v19
	v_div_fixup_f32 v2, v2, v18, 1.0
	v_pk_add_f32 v[16:17], v[16:17], 1.0 op_sel_hi:[1,0]
	v_pk_mul_f32 v[2:3], v[20:21], v[2:3]
	v_div_scale_f32 v19, s[4:5], v17, v17, 1.0
	v_rcp_f32_e32 v33, v19
	v_pk_mul_f32 v[2:3], v[4:5], v[2:3]
	v_fma_f32 v4, -v19, v33, 1.0
	v_fmac_f32_e32 v33, v4, v33
	v_div_scale_f32 v4, vcc, 1.0, v17, 1.0
	v_mul_f32_e32 v5, v4, v33
	v_fma_f32 v18, -v19, v5, v4
	v_fmac_f32_e32 v5, v18, v33
	v_div_scale_f32 v18, s[4:5], v16, v16, 1.0
	v_fma_f32 v4, -v19, v5, v4
	v_rcp_f32_e32 v19, v18
	v_div_fmas_f32 v4, v4, v33, v5
	v_div_fixup_f32 v5, v4, v17, 1.0
	v_cvt_pk_bf16_f32 v2, v2, v3
	v_fma_f32 v4, -v18, v19, 1.0
	v_fmac_f32_e32 v19, v4, v19
	v_div_scale_f32 v4, vcc, 1.0, v16, 1.0
	v_mul_f32_e32 v17, v4, v19
	v_fma_f32 v20, -v18, v17, v4
	v_fmac_f32_e32 v17, v20, v19
	v_fma_f32 v4, -v18, v17, v4
	v_div_fmas_f32 v4, v4, v19, v17
	v_mul_f32_e32 v17, 0xbfb8aa3b, v24
	v_exp_f32_e32 v18, v17
	v_mul_f32_e32 v17, 0xbfb8aa3b, v25
	v_exp_f32_e32 v19, v17
	v_div_fixup_f32 v4, v4, v16, 1.0
	v_pk_mul_f32 v[4:5], v[22:23], v[4:5]
	s_nop 0
	v_pk_mul_f32 v[4:5], v[6:7], v[4:5]
	v_pk_add_f32 v[6:7], v[18:19], 1.0 op_sel_hi:[1,0]
	v_cvt_pk_bf16_f32 v3, v4, v5
	v_div_scale_f32 v16, s[4:5], v7, v7, 1.0
	v_rcp_f32_e32 v17, v16
	ds_write2_b64 v32, v[0:1], v[2:3] offset0:72 offset1:74
	v_div_scale_f32 v4, s[4:5], v6, v6, 1.0
	v_fma_f32 v0, -v16, v17, 1.0
	v_fmac_f32_e32 v17, v0, v17
	v_div_scale_f32 v0, vcc, 1.0, v7, 1.0
	v_mul_f32_e32 v1, v0, v17
	v_fma_f32 v2, -v16, v1, v0
	v_rcp_f32_e32 v5, v4
	v_fmac_f32_e32 v1, v2, v17
	v_fma_f32 v0, -v16, v1, v0
	v_div_fmas_f32 v0, v0, v17, v1
	v_div_fixup_f32 v1, v0, v7, 1.0
	v_fma_f32 v0, -v4, v5, 1.0
	v_fmac_f32_e32 v5, v0, v5
	v_div_scale_f32 v0, vcc, 1.0, v6, 1.0
	v_mul_f32_e32 v7, v0, v5
	v_fma_f32 v2, -v4, v7, v0
	v_fmac_f32_e32 v7, v2, v5
	v_mul_f32_e32 v2, 0xbfb8aa3b, v26
	v_mul_f32_e32 v3, 0xbfb8aa3b, v27
	v_exp_f32_e32 v2, v2
	v_exp_f32_e32 v3, v3
	v_fma_f32 v0, -v4, v7, v0
	v_div_fmas_f32 v0, v0, v5, v7
	v_div_fixup_f32 v0, v0, v6, 1.0
	v_pk_add_f32 v[2:3], v[2:3], 1.0 op_sel_hi:[1,0]
	v_pk_mul_f32 v[0:1], v[24:25], v[0:1]
	v_div_scale_f32 v4, s[4:5], v3, v3, 1.0
	v_rcp_f32_e32 v5, v4
	v_pk_mul_f32 v[0:1], v[8:9], v[0:1]
	v_fma_f32 v6, -v4, v5, 1.0
	v_fmac_f32_e32 v5, v6, v5
	v_div_scale_f32 v6, vcc, 1.0, v3, 1.0
	v_mul_f32_e32 v7, v6, v5
	v_fma_f32 v8, -v4, v7, v6
	v_fmac_f32_e32 v7, v8, v5
	v_fma_f32 v4, -v4, v7, v6
	v_div_scale_f32 v6, s[4:5], v2, v2, 1.0
	v_rcp_f32_e32 v8, v6
	v_div_fmas_f32 v4, v4, v5, v7
	v_div_fixup_f32 v3, v4, v3, 1.0
	v_cvt_pk_bf16_f32 v0, v0, v1
	v_fma_f32 v4, -v6, v8, 1.0
	v_fmac_f32_e32 v8, v4, v8
	v_div_scale_f32 v4, vcc, 1.0, v2, 1.0
	v_mul_f32_e32 v7, v4, v8
	v_fma_f32 v5, -v6, v7, v4
	v_fmac_f32_e32 v7, v5, v8
	v_fma_f32 v6, -v6, v7, v4
	v_mul_f32_e32 v4, 0xbfb8aa3b, v28
	v_mul_f32_e32 v5, 0xbfb8aa3b, v29
	v_exp_f32_e32 v4, v4
	v_exp_f32_e32 v5, v5
	v_div_fmas_f32 v6, v6, v8, v7
	v_div_fixup_f32 v2, v6, v2, 1.0
	v_pk_mul_f32 v[2:3], v[26:27], v[2:3]
	v_pk_add_f32 v[4:5], v[4:5], 1.0 op_sel_hi:[1,0]
	v_pk_mul_f32 v[2:3], v[10:11], v[2:3]
	v_div_scale_f32 v6, s[4:5], v5, v5, 1.0
	v_rcp_f32_e32 v7, v6
	v_cvt_pk_bf16_f32 v1, v2, v3
	v_fma_f32 v2, -v6, v7, 1.0
	v_fmac_f32_e32 v7, v2, v7
	v_div_scale_f32 v2, vcc, 1.0, v5, 1.0
	v_mul_f32_e32 v3, v2, v7
	v_fma_f32 v8, -v6, v3, v2
	v_fmac_f32_e32 v3, v8, v7
	v_div_scale_f32 v8, s[4:5], v4, v4, 1.0
	v_rcp_f32_e32 v9, v8
	v_fma_f32 v2, -v6, v3, v2
	v_div_fmas_f32 v2, v2, v7, v3
	v_div_fixup_f32 v3, v2, v5, 1.0
	v_fma_f32 v2, -v8, v9, 1.0
	v_fmac_f32_e32 v9, v2, v9
	v_div_scale_f32 v2, vcc, 1.0, v4, 1.0
	v_mul_f32_e32 v5, v2, v9
	v_fma_f32 v6, -v8, v5, v2
	v_fmac_f32_e32 v5, v6, v9
	v_mul_f32_e32 v6, 0xbfb8aa3b, v30
	v_mul_f32_e32 v7, 0xbfb8aa3b, v31
	v_exp_f32_e32 v6, v6
	v_exp_f32_e32 v7, v7
	v_fma_f32 v2, -v8, v5, v2
	v_div_fmas_f32 v2, v2, v9, v5
	v_div_fixup_f32 v2, v2, v4, 1.0
	v_pk_add_f32 v[6:7], v[6:7], 1.0 op_sel_hi:[1,0]
	v_pk_mul_f32 v[2:3], v[28:29], v[2:3]
	v_div_scale_f32 v5, s[4:5], v7, v7, 1.0
	v_rcp_f32_e32 v8, v5
	v_pk_mul_f32 v[2:3], v[12:13], v[2:3]
	v_fma_f32 v4, -v5, v8, 1.0
	v_fmac_f32_e32 v8, v4, v8
	v_div_scale_f32 v4, vcc, 1.0, v7, 1.0
	v_mul_f32_e32 v9, v4, v8
	v_fma_f32 v10, -v5, v9, v4
	v_fmac_f32_e32 v9, v10, v8
	v_div_scale_f32 v10, s[4:5], v6, v6, 1.0
	v_rcp_f32_e32 v11, v10
	v_fma_f32 v4, -v5, v9, v4
	v_div_fmas_f32 v4, v4, v8, v9
	v_div_fixup_f32 v5, v4, v7, 1.0
	v_fma_f32 v4, -v10, v11, 1.0
	v_fmac_f32_e32 v11, v4, v11
	v_div_scale_f32 v4, vcc, 1.0, v6, 1.0
	v_mul_f32_e32 v7, v4, v11
	v_fma_f32 v8, -v10, v7, v4
	v_fmac_f32_e32 v7, v8, v11
	v_fma_f32 v4, -v10, v7, v4
	v_div_fmas_f32 v4, v4, v11, v7
	v_div_fixup_f32 v4, v4, v6, 1.0
	v_pk_mul_f32 v[4:5], v[30:31], v[4:5]
	v_cvt_pk_bf16_f32 v2, v2, v3
	v_pk_mul_f32 v[4:5], v[14:15], v[4:5]
	s_nop 0
	v_cvt_pk_bf16_f32 v3, v4, v5
	ds_write2_b64 v32, v[0:1], v[2:3] offset0:76 offset1:78
	s_waitcnt lgkmcnt(0)
	v_mov_b32_e32 v1, v220
	s_barrier
	s_nop 0
	v_cmp_gt_i32_e32 vcc, s69, v1
	s_and_saveexec_b64 s[4:5], vcc
	s_cbranch_execz .LBB0_1189
	s_lshl_b32 s6, s79, 8
	s_add_u32 s6, s77, s6
	v_lshlrev_b32_e32 v0, 4, v1
	s_addc_u32 s7, s78, 0
	v_and_b32_e32 v184, 0xf0, v0
	v_or_b32_e32 v0, 0x10000, v184
	v_lshl_add_u64 v[2:3], s[6:7], 0, v[184:185]
	s_mov_b64 s[6:7], 0
